# FFN-up: remaining conv groups as DPP fmac chains, last-iteration weights read from prefetch registers; FFN-down halo loads hoisted; cross q-norm sum of squares slimmed
# speedup vs baseline: 1.0084x; 1.0005x over previous
; __device__ __forceinline__ unsigned pk2(float lo, float hi) { f32x2_t v = {lo, hi}; bf16x2_t b = __builtin_convertvector(v, bf16x2_t); return __builtin_bit_cast(unsigned, b); }
; __device__ __forceinline__ float pair_sum(float v) { auto r = __builtin_amdgcn_permlane32_swap(__float_as_uint(v), __float_as_uint(v), false, false); return __uint_as_float(r[0]) + __uint_as_float(r[1]); }
; __device__ __forceinline__ void cross_unit(lbyte* lds, bf16* CQ, const bf16* CKV, const float* gq, const float* gk, int layer, int b, int hc, int qblk0, int qstep, int nq) {
;     ...
;     for (int qi = 0; qi < nq; ++qi) { const int qblk = qblk0 + qi * qstep;
;     const size_t row = (size_t)b * SEQ + qblk * 256 + 32 * wid + l31;
;     bf16* qrow = CQ + row * 512 + hc * 128;
;     s16x8 qf[8];
; #pragma unroll
;     for (int c = 0; c < 8; ++c) qf[c] = *(const s16x8*)(qrow + 16 * c + 8 * h);
;     { float ss = 0.f;
; #pragma unroll
;       for (int c = 0; c < 8; ++c)
; #pragma unroll
;           for (int e2 = 0; e2 < 8; ++e2) { const float f = bf2f((unsigned short)qf[c][e2]); ss += f * f; }
;       ss = pair_sum(ss); const float rn = __builtin_amdgcn_rsqf(ss * (1.0f / 128.0f) + 1e-6f);
; #pragma unroll
;       for (int c = 0; c < 8; ++c) { const f32x4 ga = *(const f32x4*)(gq + 16 * c + 8 * h), gb = *(const f32x4*)(gq + 16 * c + 8 * h + 4); u32x4 w;
;           w.x = pk2(bf2f((unsigned short)qf[c][0]) * rn * ga[0], bf2f((unsigned short)qf[c][1]) * rn * ga[1]); w.y = pk2(bf2f((unsigned short)qf[c][2]) * rn * ga[2], bf2f((unsigned short)qf[c][3]) * rn * ga[3]);
;           w.z = pk2(bf2f((unsigned short)qf[c][4]) * rn * gb[0], bf2f((unsigned short)qf[c][5]) * rn * gb[1]); w.w = pk2(bf2f((unsigned short)qf[c][6]) * rn * gb[2], bf2f((unsigned short)qf[c][7]) * rn * gb[3]);
;           qf[c] = __builtin_bit_cast(s16x8, w); } }
.LBB0_988:
	v_readlane_b32 s1, v254, 63
	s_mul_i32 s1, s0, s1
	s_add_i32 s1, s1, s68
	s_lshl_b32 s4, s1, 8
	s_ashr_i32 s5, s4, 31
	v_lshl_add_u64 v[2:3], v[148:149], 0, s[4:5]
	v_lshlrev_b64 v[2:3], 10, v[2:3]
	v_lshl_add_u64 v[154:155], v[152:153], 0, v[2:3]
	global_load_dwordx4 v[64:67], v[154:155], off offset:224
	global_load_dwordx4 v[72:75], v[154:155], off offset:192
	global_load_dwordx4 v[80:83], v[154:155], off offset:160
	global_load_dwordx4 v[88:91], v[154:155], off offset:128
	global_load_dwordx4 v[96:99], v[154:155], off offset:96
	global_load_dwordx4 v[100:103], v[154:155], off offset:64
	global_load_dwordx4 v[104:107], v[154:155], off offset:32
	global_load_dwordx4 v[108:111], v[154:155], off
	global_load_dwordx4 v[50:53], v[150:151], off offset:16
	global_load_dwordx4 v[54:57], v[150:151], off
	global_load_dwordx4 v[42:45], v[150:151], off offset:80
	global_load_dwordx4 v[46:49], v[150:151], off offset:64
	global_load_dwordx4 v[34:37], v[150:151], off offset:144
	global_load_dwordx4 v[38:41], v[150:151], off offset:128
	global_load_dwordx4 v[26:29], v[150:151], off offset:208
	global_load_dwordx4 v[30:33], v[150:151], off offset:192
	global_load_dwordx4 v[18:21], v[150:151], off offset:272
	global_load_dwordx4 v[22:25], v[150:151], off offset:256
	global_load_dwordx4 v[10:13], v[150:151], off offset:336
	global_load_dwordx4 v[14:17], v[150:151], off offset:320
	global_load_dwordx4 v[2:5], v[150:151], off offset:400
	global_load_dwordx4 v[6:9], v[150:151], off offset:384
	global_load_dwordx4 v[126:129], v[150:151], off offset:464
	global_load_dwordx4 v[130:133], v[150:151], off offset:448
	s_mov_b32 s1, 8
	v_mov_b32_e32 v158, 0
	v_mov_b32_e32 v162, 0xf149f2ca
	v_mov_b32_e32 v159, v157
	v_mov_b32_e32 v160, v156
	s_waitcnt vmcnt(23)
	v_and_b32_e32 v59, 0xffff0000, v67
	v_lshlrev_b32_e32 v58, 16, v67
	v_and_b32_e32 v61, 0xffff0000, v66
	v_lshlrev_b32_e32 v60, 16, v66
	s_waitcnt vmcnt(19)
	v_and_b32_e32 v95, 0xffff0000, v97
	v_lshlrev_b32_e32 v94, 16, v97
	v_and_b32_e32 v113, 0xffff0000, v96
	s_waitcnt vmcnt(16)
	v_and_b32_e32 v97, 0xffff0000, v108
	v_lshlrev_b32_e32 v112, 16, v96
	v_lshlrev_b32_e32 v96, 16, v108
	v_and_b32_e32 v67, 0xffff0000, v75
	v_lshlrev_b32_e32 v66, 16, v75
	v_and_b32_e32 v69, 0xffff0000, v74
	v_lshlrev_b32_e32 v68, 16, v74
	v_and_b32_e32 v75, 0xffff0000, v83
	v_lshlrev_b32_e32 v74, 16, v83
	v_and_b32_e32 v77, 0xffff0000, v82
	v_lshlrev_b32_e32 v76, 16, v82
	v_and_b32_e32 v83, 0xffff0000, v91
	v_lshlrev_b32_e32 v82, 16, v91
	v_and_b32_e32 v85, 0xffff0000, v90
	v_lshlrev_b32_e32 v84, 16, v90
	v_and_b32_e32 v91, 0xffff0000, v99
	v_lshlrev_b32_e32 v90, 16, v99
	v_and_b32_e32 v93, 0xffff0000, v98
	v_lshlrev_b32_e32 v92, 16, v98
	v_and_b32_e32 v115, 0xffff0000, v103
	v_lshlrev_b32_e32 v114, 16, v103
	v_and_b32_e32 v117, 0xffff0000, v102
	v_lshlrev_b32_e32 v116, 16, v102
	v_and_b32_e32 v119, 0xffff0000, v101
	v_lshlrev_b32_e32 v118, 16, v101
	v_and_b32_e32 v121, 0xffff0000, v100
	v_lshlrev_b32_e32 v120, 16, v100
	v_and_b32_e32 v123, 0xffff0000, v107
	v_lshlrev_b32_e32 v122, 16, v107
	v_and_b32_e32 v103, 0xffff0000, v106
	v_lshlrev_b32_e32 v102, 16, v106
	v_and_b32_e32 v107, 0xffff0000, v105
	v_lshlrev_b32_e32 v106, 16, v105
	v_and_b32_e32 v101, 0xffff0000, v104
	v_lshlrev_b32_e32 v100, 16, v104
	v_and_b32_e32 v105, 0xffff0000, v111
	v_lshlrev_b32_e32 v104, 16, v111
	v_and_b32_e32 v99, 0xffff0000, v110
	v_lshlrev_b32_e32 v98, 16, v110
	v_and_b32_e32 v111, 0xffff0000, v109
	v_lshlrev_b32_e32 v110, 16, v109
	v_pk_mul_f32 v[108:109], v[96:97], v[96:97]
	v_pk_fma_f32 v[108:109], v[110:111], v[110:111], v[108:109]
	v_and_b32_e32 v87, 0xffff0000, v89
	v_pk_fma_f32 v[108:109], v[98:99], v[98:99], v[108:109]
	v_pk_fma_f32 v[108:109], v[104:105], v[104:105], v[108:109]
	v_pk_fma_f32 v[108:109], v[100:101], v[100:101], v[108:109]
	v_pk_fma_f32 v[108:109], v[106:107], v[106:107], v[108:109]
	v_pk_fma_f32 v[108:109], v[102:103], v[102:103], v[108:109]
	v_pk_fma_f32 v[108:109], v[122:123], v[122:123], v[108:109]
	v_pk_fma_f32 v[108:109], v[120:121], v[120:121], v[108:109]
	v_pk_fma_f32 v[108:109], v[118:119], v[118:119], v[108:109]
	v_pk_fma_f32 v[108:109], v[116:117], v[116:117], v[108:109]
	v_pk_fma_f32 v[108:109], v[114:115], v[114:115], v[108:109]
	v_pk_fma_f32 v[108:109], v[112:113], v[112:113], v[108:109]
	v_pk_fma_f32 v[108:109], v[94:95], v[94:95], v[108:109]
	v_pk_fma_f32 v[108:109], v[92:93], v[92:93], v[108:109]
	v_pk_fma_f32 v[108:109], v[90:91], v[90:91], v[108:109]
	v_lshlrev_b32_e32 v86, 16, v89
	v_and_b32_e32 v89, 0xffff0000, v88
	v_lshlrev_b32_e32 v88, 16, v88
	v_pk_fma_f32 v[108:109], v[88:89], v[88:89], v[108:109]
	v_pk_fma_f32 v[108:109], v[86:87], v[86:87], v[108:109]
	v_pk_fma_f32 v[108:109], v[84:85], v[84:85], v[108:109]
	v_pk_fma_f32 v[108:109], v[82:83], v[82:83], v[108:109]
	v_and_b32_e32 v79, 0xffff0000, v81
	v_lshlrev_b32_e32 v78, 16, v81
	v_and_b32_e32 v81, 0xffff0000, v80
	v_lshlrev_b32_e32 v80, 16, v80
	v_pk_fma_f32 v[108:109], v[80:81], v[80:81], v[108:109]
	v_pk_fma_f32 v[108:109], v[78:79], v[78:79], v[108:109]
	v_pk_fma_f32 v[108:109], v[76:77], v[76:77], v[108:109]
	v_pk_fma_f32 v[108:109], v[74:75], v[74:75], v[108:109]
	v_and_b32_e32 v71, 0xffff0000, v73
	v_lshlrev_b32_e32 v70, 16, v73
	v_and_b32_e32 v73, 0xffff0000, v72
	v_lshlrev_b32_e32 v72, 16, v72
	v_pk_fma_f32 v[108:109], v[72:73], v[72:73], v[108:109]
	v_pk_fma_f32 v[108:109], v[70:71], v[70:71], v[108:109]
	v_pk_fma_f32 v[108:109], v[68:69], v[68:69], v[108:109]
	v_pk_fma_f32 v[108:109], v[66:67], v[66:67], v[108:109]
	v_and_b32_e32 v63, 0xffff0000, v65
	v_lshlrev_b32_e32 v62, 16, v65
	v_and_b32_e32 v65, 0xffff0000, v64
	v_lshlrev_b32_e32 v64, 16, v64
	v_pk_fma_f32 v[108:109], v[64:65], v[64:65], v[108:109]
	v_pk_fma_f32 v[108:109], v[62:63], v[62:63], v[108:109]
	v_pk_fma_f32 v[108:109], v[60:61], v[60:61], v[108:109]
	v_pk_fma_f32 v[108:109], v[58:59], v[58:59], v[108:109]
	v_add_f32_e32 v108, v108, v109
	v_mov_b32_e32 v0, v108
	s_nop 1
	v_permlane32_swap_b32_e32 v108, v0
	v_add_f32_e32 v0, v108, v0
	v_fmamk_f32 v0, v0, 0x3c000000, v233
	v_rsq_f32_e32 v0, v0
	s_nop 0
	v_pk_mul_f32 v[96:97], v[0:1], v[96:97] op_sel_hi:[0,1]
	s_waitcnt vmcnt(14)
; __device__ __forceinline__ unsigned pk2(float lo, float hi) { f32x2_t v = {lo, hi}; bf16x2_t b = __builtin_convertvector(v, bf16x2_t); return __builtin_bit_cast(unsigned, b); }
; __device__ __forceinline__ float pair_sum(float v) { auto r = __builtin_amdgcn_permlane32_swap(__float_as_uint(v), __float_as_uint(v), false, false); return __uint_as_float(r[0]) + __uint_as_float(r[1]); }
; __device__ __forceinline__ void cross_unit(lbyte* lds, bf16* CQ, const bf16* CKV, const float* gq, const float* gk, int layer, int b, int hc, int qblk0, int qstep, int nq) {
;     ...
;       ss = pair_sum(ss); const float rn = __builtin_amdgcn_rsqf(ss * (1.0f / 128.0f) + 1e-6f);
; #pragma unroll
;       for (int c = 0; c < 8; ++c) { const f32x4 ga = *(const f32x4*)(gq + 16 * c + 8 * h), gb = *(const f32x4*)(gq + 16 * c + 8 * h + 4); u32x4 w;
;           w.x = pk2(bf2f((unsigned short)qf[c][0]) * rn * ga[0], bf2f((unsigned short)qf[c][1]) * rn * ga[1]); w.y = pk2(bf2f((unsigned short)qf[c][2]) * rn * ga[2], bf2f((unsigned short)qf[c][3]) * rn * ga[3]);
;           w.z = pk2(bf2f((unsigned short)qf[c][4]) * rn * gb[0], bf2f((unsigned short)qf[c][5]) * rn * gb[1]); w.w = pk2(bf2f((unsigned short)qf[c][6]) * rn * gb[2], bf2f((unsigned short)qf[c][7]) * rn * gb[3]);
;           qf[c] = __builtin_bit_cast(s16x8, w); } }
;     f32x16 o[4];
; #pragma unroll
;     for (int r = 0; r < 16; ++r) { o[0][r] = 0.f; o[1][r] = 0.f; o[2][r] = 0.f; o[3][r] = 0.f; }
	v_pk_mul_f32 v[54:55], v[54:55], v[96:97]
	s_nop 0
	v_cvt_pk_bf16_f32 v96, v54, v55
	v_pk_mul_f32 v[54:55], v[0:1], v[110:111] op_sel_hi:[0,1]
	v_pk_mul_f32 v[54:55], v[56:57], v[54:55]
	s_nop 0
	v_cvt_pk_bf16_f32 v97, v54, v55
	v_pk_mul_f32 v[54:55], v[0:1], v[98:99] op_sel_hi:[0,1]
	v_pk_mul_f32 v[50:51], v[50:51], v[54:55]
	s_nop 0
	v_cvt_pk_bf16_f32 v98, v50, v51
	v_pk_mul_f32 v[50:51], v[0:1], v[104:105] op_sel_hi:[0,1]
	v_pk_mul_f32 v[50:51], v[52:53], v[50:51]
	s_nop 0
	v_cvt_pk_bf16_f32 v99, v50, v51
	v_pk_mul_f32 v[50:51], v[0:1], v[100:101] op_sel_hi:[0,1]
	s_waitcnt vmcnt(12)
	v_pk_mul_f32 v[46:47], v[46:47], v[50:51]
	s_nop 0
	v_cvt_pk_bf16_f32 v100, v46, v47
	v_pk_mul_f32 v[46:47], v[0:1], v[106:107] op_sel_hi:[0,1]
	v_pk_mul_f32 v[46:47], v[48:49], v[46:47]
	s_nop 0
	v_cvt_pk_bf16_f32 v101, v46, v47
	v_pk_mul_f32 v[46:47], v[0:1], v[102:103] op_sel_hi:[0,1]
	v_pk_mul_f32 v[42:43], v[42:43], v[46:47]
	s_nop 0
	v_cvt_pk_bf16_f32 v102, v42, v43
	v_pk_mul_f32 v[42:43], v[0:1], v[122:123] op_sel_hi:[0,1]
	v_pk_mul_f32 v[42:43], v[44:45], v[42:43]
	s_nop 0
	v_cvt_pk_bf16_f32 v103, v42, v43
	v_pk_mul_f32 v[42:43], v[0:1], v[120:121] op_sel_hi:[0,1]
	s_waitcnt vmcnt(10)
	v_pk_mul_f32 v[38:39], v[38:39], v[42:43]
	s_nop 0
	v_cvt_pk_bf16_f32 v104, v38, v39
	v_pk_mul_f32 v[38:39], v[0:1], v[118:119] op_sel_hi:[0,1]
	v_pk_mul_f32 v[38:39], v[40:41], v[38:39]
	s_nop 0
	v_cvt_pk_bf16_f32 v105, v38, v39
	v_pk_mul_f32 v[38:39], v[0:1], v[116:117] op_sel_hi:[0,1]
	v_pk_mul_f32 v[34:35], v[34:35], v[38:39]
	s_nop 0
	v_cvt_pk_bf16_f32 v106, v34, v35
	v_pk_mul_f32 v[34:35], v[0:1], v[114:115] op_sel_hi:[0,1]
	v_pk_mul_f32 v[34:35], v[36:37], v[34:35]
	s_nop 0
	v_cvt_pk_bf16_f32 v107, v34, v35
	v_pk_mul_f32 v[34:35], v[0:1], v[112:113] op_sel_hi:[0,1]
	s_waitcnt vmcnt(8)
	v_pk_mul_f32 v[30:31], v[34:35], v[30:31]
	s_nop 0
	v_cvt_pk_bf16_f32 v108, v30, v31
	v_pk_mul_f32 v[30:31], v[0:1], v[94:95] op_sel_hi:[0,1]
	v_pk_mul_f32 v[30:31], v[30:31], v[32:33]
	s_nop 0
	v_cvt_pk_bf16_f32 v109, v30, v31
	v_pk_mul_f32 v[30:31], v[0:1], v[92:93] op_sel_hi:[0,1]
	v_pk_mul_f32 v[26:27], v[30:31], v[26:27]
	s_nop 0
	v_cvt_pk_bf16_f32 v110, v26, v27
	v_pk_mul_f32 v[26:27], v[0:1], v[90:91] op_sel_hi:[0,1]
	v_pk_mul_f32 v[26:27], v[26:27], v[28:29]
	s_nop 0
	v_cvt_pk_bf16_f32 v111, v26, v27
	v_pk_mul_f32 v[26:27], v[0:1], v[88:89] op_sel_hi:[0,1]
	s_waitcnt vmcnt(6)
	v_pk_mul_f32 v[22:23], v[26:27], v[22:23]
	s_nop 0
	v_cvt_pk_bf16_f32 v112, v22, v23
	v_pk_mul_f32 v[22:23], v[0:1], v[86:87] op_sel_hi:[0,1]
	v_pk_mul_f32 v[22:23], v[22:23], v[24:25]
	s_nop 0
	v_cvt_pk_bf16_f32 v113, v22, v23
	v_pk_mul_f32 v[22:23], v[0:1], v[84:85] op_sel_hi:[0,1]
	v_pk_mul_f32 v[18:19], v[22:23], v[18:19]
	s_nop 0
	v_cvt_pk_bf16_f32 v114, v18, v19
	v_pk_mul_f32 v[18:19], v[0:1], v[82:83] op_sel_hi:[0,1]
	v_pk_mul_f32 v[18:19], v[18:19], v[20:21]
	s_nop 0
	v_cvt_pk_bf16_f32 v115, v18, v19
	v_pk_mul_f32 v[18:19], v[0:1], v[80:81] op_sel_hi:[0,1]
	s_waitcnt vmcnt(4)
	v_pk_mul_f32 v[14:15], v[18:19], v[14:15]
	s_nop 0
	v_cvt_pk_bf16_f32 v116, v14, v15
	v_pk_mul_f32 v[14:15], v[0:1], v[78:79] op_sel_hi:[0,1]
	v_pk_mul_f32 v[14:15], v[14:15], v[16:17]
	s_nop 0
	v_cvt_pk_bf16_f32 v117, v14, v15
	v_pk_mul_f32 v[14:15], v[0:1], v[76:77] op_sel_hi:[0,1]
	v_pk_mul_f32 v[10:11], v[14:15], v[10:11]
	v_mov_b32_e32 v14, v1
	v_cvt_pk_bf16_f32 v118, v10, v11
	v_pk_mul_f32 v[10:11], v[0:1], v[74:75] op_sel_hi:[0,1]
	v_pk_mul_f32 v[10:11], v[10:11], v[12:13]
	v_mov_b32_e32 v15, v1
	v_cvt_pk_bf16_f32 v119, v10, v11
	v_pk_mul_f32 v[10:11], v[0:1], v[72:73] op_sel_hi:[0,1]
	s_waitcnt vmcnt(2)
	v_pk_mul_f32 v[6:7], v[10:11], v[6:7]
	v_mov_b32_e32 v10, v1
	v_cvt_pk_bf16_f32 v120, v6, v7
	v_pk_mul_f32 v[6:7], v[0:1], v[70:71] op_sel_hi:[0,1]
	v_pk_mul_f32 v[6:7], v[6:7], v[8:9]
	v_mov_b32_e32 v8, v1
	v_cvt_pk_bf16_f32 v121, v6, v7
	v_pk_mul_f32 v[6:7], v[0:1], v[68:69] op_sel_hi:[0,1]
	v_pk_mul_f32 v[2:3], v[6:7], v[2:3]
	v_mov_b32_e32 v6, v1
	v_cvt_pk_bf16_f32 v122, v2, v3
	v_pk_mul_f32 v[2:3], v[0:1], v[66:67] op_sel_hi:[0,1]
	v_pk_mul_f32 v[2:3], v[2:3], v[4:5]
	v_mov_b32_e32 v4, v1
	v_cvt_pk_bf16_f32 v123, v2, v3
	v_pk_mul_f32 v[2:3], v[0:1], v[64:65] op_sel_hi:[0,1]
	s_waitcnt vmcnt(0)
	v_pk_mul_f32 v[2:3], v[2:3], v[130:131]
	v_mov_b32_e32 v5, v1
	v_cvt_pk_bf16_f32 v124, v2, v3
	v_pk_mul_f32 v[2:3], v[0:1], v[62:63] op_sel_hi:[0,1]
	v_pk_mul_f32 v[2:3], v[2:3], v[132:133]
	v_mov_b32_e32 v7, v1
	v_cvt_pk_bf16_f32 v125, v2, v3
	v_pk_mul_f32 v[2:3], v[0:1], v[60:61] op_sel_hi:[0,1]
	v_pk_mul_f32 v[2:3], v[2:3], v[126:127]
	v_mov_b32_e32 v9, v1
	v_cvt_pk_bf16_f32 v126, v2, v3
	v_pk_mul_f32 v[2:3], v[0:1], v[58:59] op_sel_hi:[0,1]
	v_pk_mul_f32 v[2:3], v[2:3], v[128:129]
	v_mov_b32_e32 v0, v1
	v_cvt_pk_bf16_f32 v127, v2, v3
	v_mov_b32_e32 v2, v1
	v_mov_b32_e32 v3, v1
	v_mov_b32_e32 v11, v1
	v_mov_b32_e32 v12, v1
	v_mov_b32_e32 v13, v1
	v_mov_b64_e32 v[30:31], v[14:15]
	v_mov_b64_e32 v[46:47], v[14:15]
	v_mov_b64_e32 v[62:63], v[14:15]
	v_mov_b64_e32 v[78:79], v[14:15]
	v_mov_b64_e32 v[28:29], v[12:13]
	v_mov_b64_e32 v[26:27], v[10:11]
	v_mov_b64_e32 v[24:25], v[8:9]
	v_mov_b64_e32 v[22:23], v[6:7]
	v_mov_b64_e32 v[20:21], v[4:5]
	v_mov_b64_e32 v[18:19], v[2:3]
	v_mov_b64_e32 v[16:17], v[0:1]
	v_mov_b64_e32 v[44:45], v[12:13]
	v_mov_b64_e32 v[42:43], v[10:11]
	v_mov_b64_e32 v[40:41], v[8:9]
	v_mov_b64_e32 v[38:39], v[6:7]
	v_mov_b64_e32 v[36:37], v[4:5]
	v_mov_b64_e32 v[34:35], v[2:3]
	v_mov_b64_e32 v[32:33], v[0:1]
	v_mov_b64_e32 v[60:61], v[12:13]
	v_mov_b64_e32 v[58:59], v[10:11]
	v_mov_b64_e32 v[56:57], v[8:9]
	v_mov_b64_e32 v[54:55], v[6:7]
	v_mov_b64_e32 v[52:53], v[4:5]
	v_mov_b64_e32 v[50:51], v[2:3]
	v_mov_b64_e32 v[48:49], v[0:1]
	v_mov_b64_e32 v[76:77], v[12:13]
	v_mov_b64_e32 v[74:75], v[10:11]
	v_mov_b64_e32 v[72:73], v[8:9]
	v_mov_b64_e32 v[70:71], v[6:7]
	v_mov_b64_e32 v[68:69], v[4:5]
	v_mov_b64_e32 v[66:67], v[2:3]
	v_mov_b64_e32 v[64:65], v[0:1]

; #define PG8_LAS __attribute__((address_space(3)))
;     __device__ __forceinline__ void operator()(f32x4 (&acc)[2][2][4][2], const Unit& u, int ui, int wr, int wc, int fr_, int fq_) const {
;     ...
; #pragma unroll
;         for (int bj = 0; bj < 2; ++bj)
; #pragma unroll
;             for (int n = 0; n < 2; ++n) { const int ch = bj * 2816 + fbase + 4 * n;
;                 const f32x4 w0 = *(const f32x4*)(cw + ch), w1 = *(const f32x4*)(cw + 5632 + ch), w2 = *(const f32x4*)(cw + 2 * 5632 + ch), bb = *(const f32x4*)(cb + ch);
; #pragma unroll
;                 for (int ai = 0; ai < 2; ++ai) { const int kb = 2 * ai + wr;
;                     f32x4 c62 = (f32x4){0.f, 0.f, 0.f, 0.f}, c63 = c62;
;                     if (kb > 0) { c62 = *(const PG8_LAS f32x4*)(exch + (((kb - 1) * 2 + 0) * 256 + bj * HALF + 32 * wc + 8 * fq + 4 * n)); c63 = *(const PG8_LAS f32x4*)(exch + (((kb - 1) * 2 + 1) * 256 + bj * HALF + 32 * wc + 8 * fq + 4 * n)); }
; #pragma unroll
;                     for (int m = 3; m >= 0; --m) { f32x4 cur = acc[ai][bj][m][n], res;
; #pragma unroll
;                         for (int j = 0; j < 4; ++j) { const float c = cur[j]; const float pv = (m > 0) ? acc[ai][bj][m > 0 ? m - 1 : 0][n][j] : (fr == 15 ? c63[j] : c62[j]); float t1, t2;
;                             asm volatile("s_nop 1\n\tv_mov_b32_dpp %0, %3 row_ror:1 row_mask:0xf bank_mask:0xf\n\tv_mov_b32_dpp %1, %3 row_ror:2 row_mask:0xf bank_mask:0xf\n\t"
;                                          "v_mov_b32_dpp %0, %2 row_shr:1 row_mask:0xf bank_mask:0xf\n\tv_mov_b32_dpp %1, %2 row_shr:2 row_mask:0xf bank_mask:0xf"
;                                          : "=&v"(t1), "=&v"(t2) : "v"(c), "v"(pv));
;                             res[j] = bb[j] + w0[j] * t2 + w1[j] * t1 + w2[j] * c; }
;                         asm volatile("" : "+v"(res[0]), "+v"(res[1]), "+v"(res[2]), "+v"(res[3]));
;                         acc[ai][bj][m][n] = res; } }
.LBB0_1186:
	v_pk_mul_f32 v[102:103], v[102:103], v[196:197] op_sel_hi:[1,0]
	v_pk_mul_f32 v[104:105], v[104:105], v[196:197] op_sel_hi:[1,0]
	v_pk_mul_f32 v[106:107], v[106:107], v[194:195] op_sel_hi:[1,0]
	s_waitcnt vmcnt(0)
	v_mov_b32_e32 v211, v30
	v_fmac_f32_dpp v211, v152, v134 row_shr:2 row_mask:0xf bank_mask:0xf
	v_fmac_f32_dpp v211, v102, v134 row_shl:14 row_mask:0xf bank_mask:0xf
	v_fmac_f32_dpp v211, v152, v118 row_shr:1 row_mask:0xf bank_mask:0xf
	v_fmac_f32_dpp v211, v102, v118 row_shl:15 row_mask:0xf bank_mask:0xf
	v_fmac_f32_e32 v211, v152, v130
	v_pk_mul_f32 v[108:109], v[108:109], v[194:195] op_sel_hi:[1,0]
	v_mov_b32_e32 v212, v31
	v_fmac_f32_dpp v212, v153, v135 row_shr:2 row_mask:0xf bank_mask:0xf
	v_fmac_f32_dpp v212, v103, v135 row_shl:14 row_mask:0xf bank_mask:0xf
	v_fmac_f32_dpp v212, v153, v119 row_shr:1 row_mask:0xf bank_mask:0xf
	v_fmac_f32_dpp v212, v103, v119 row_shl:15 row_mask:0xf bank_mask:0xf
	v_fmac_f32_e32 v212, v153, v131
	v_cmp_eq_u32_e64 s[8:9], 15, v210
	v_mov_b32_e32 v152, v32
	v_fmac_f32_dpp v152, v154, v136 row_shr:2 row_mask:0xf bank_mask:0xf
	v_fmac_f32_dpp v152, v104, v136 row_shl:14 row_mask:0xf bank_mask:0xf
	v_fmac_f32_dpp v152, v154, v120 row_shr:1 row_mask:0xf bank_mask:0xf
	v_fmac_f32_dpp v152, v104, v120 row_shl:15 row_mask:0xf bank_mask:0xf
	v_fmac_f32_e32 v152, v154, v132
	s_andn2_b64 vcc, exec, s[40:41]
	v_mov_b32_e32 v153, v33
	v_fmac_f32_dpp v153, v155, v137 row_shr:2 row_mask:0xf bank_mask:0xf
	v_fmac_f32_dpp v153, v105, v137 row_shl:14 row_mask:0xf bank_mask:0xf
	v_fmac_f32_dpp v153, v155, v121 row_shr:1 row_mask:0xf bank_mask:0xf
	v_fmac_f32_dpp v153, v105, v121 row_shl:15 row_mask:0xf bank_mask:0xf
	v_fmac_f32_e32 v153, v155, v133
	v_lshl_add_u32 v227, v143, 2, s86
	v_mov_b32_e32 v213, v30
	v_fmac_f32_dpp v213, v102, v134 row_shr:2 row_mask:0xf bank_mask:0xf
	v_fmac_f32_dpp v213, v106, v134 row_shl:14 row_mask:0xf bank_mask:0xf
	v_fmac_f32_dpp v213, v102, v118 row_shr:1 row_mask:0xf bank_mask:0xf
	v_fmac_f32_dpp v213, v106, v118 row_shl:15 row_mask:0xf bank_mask:0xf
	v_fmac_f32_e32 v213, v102, v130
	v_mov_b32_e32 v143, 0
	v_mov_b32_e32 v216, v31
	v_fmac_f32_dpp v216, v103, v135 row_shr:2 row_mask:0xf bank_mask:0xf
	v_fmac_f32_dpp v216, v107, v135 row_shl:14 row_mask:0xf bank_mask:0xf
	v_fmac_f32_dpp v216, v103, v119 row_shr:1 row_mask:0xf bank_mask:0xf
	v_fmac_f32_dpp v216, v107, v119 row_shl:15 row_mask:0xf bank_mask:0xf
	v_fmac_f32_e32 v216, v103, v131
	s_nop 0
	v_mov_b32_e32 v154, v32
	v_fmac_f32_dpp v154, v104, v136 row_shr:2 row_mask:0xf bank_mask:0xf
	v_fmac_f32_dpp v154, v108, v136 row_shl:14 row_mask:0xf bank_mask:0xf
	v_fmac_f32_dpp v154, v104, v120 row_shr:1 row_mask:0xf bank_mask:0xf
	v_fmac_f32_dpp v154, v108, v120 row_shl:15 row_mask:0xf bank_mask:0xf
	v_fmac_f32_e32 v154, v104, v132
	v_mov_b32_e32 v214, v33
	v_fmac_f32_dpp v214, v105, v137 row_shr:2 row_mask:0xf bank_mask:0xf
	v_fmac_f32_dpp v214, v109, v137 row_shl:14 row_mask:0xf bank_mask:0xf
	v_fmac_f32_dpp v214, v105, v121 row_shr:1 row_mask:0xf bank_mask:0xf
	v_fmac_f32_dpp v214, v109, v121 row_shl:15 row_mask:0xf bank_mask:0xf
	v_fmac_f32_e32 v214, v105, v133
	s_waitcnt lgkmcnt(0)
	v_cndmask_b32_e64 v105, v144, v148, s[8:9]
	v_mov_b32_e32 v218, v30
	v_fmac_f32_dpp v218, v106, v134 row_shr:2 row_mask:0xf bank_mask:0xf
	v_fmac_f32_dpp v218, v138, v134 row_shl:14 row_mask:0xf bank_mask:0xf
	v_fmac_f32_dpp v218, v106, v118 row_shr:1 row_mask:0xf bank_mask:0xf
	v_fmac_f32_dpp v218, v138, v118 row_shl:15 row_mask:0xf bank_mask:0xf
	v_fmac_f32_e32 v218, v106, v130
	v_mov_b32_e32 v220, v31
	v_fmac_f32_dpp v220, v107, v135 row_shr:2 row_mask:0xf bank_mask:0xf
	v_fmac_f32_dpp v220, v139, v135 row_shl:14 row_mask:0xf bank_mask:0xf
	v_fmac_f32_dpp v220, v107, v119 row_shr:1 row_mask:0xf bank_mask:0xf
	v_fmac_f32_dpp v220, v139, v119 row_shl:15 row_mask:0xf bank_mask:0xf
	v_fmac_f32_e32 v220, v107, v131
	v_mov_b32_e32 v217, v32
	v_fmac_f32_dpp v217, v108, v136 row_shr:2 row_mask:0xf bank_mask:0xf
	v_fmac_f32_dpp v217, v140, v136 row_shl:14 row_mask:0xf bank_mask:0xf
	v_fmac_f32_dpp v217, v108, v120 row_shr:1 row_mask:0xf bank_mask:0xf
	v_fmac_f32_dpp v217, v140, v120 row_shl:15 row_mask:0xf bank_mask:0xf
	v_fmac_f32_e32 v217, v108, v132
	v_mov_b32_e32 v219, v33
	v_fmac_f32_dpp v219, v109, v137 row_shr:2 row_mask:0xf bank_mask:0xf
	v_fmac_f32_dpp v219, v141, v137 row_shl:14 row_mask:0xf bank_mask:0xf
	v_fmac_f32_dpp v219, v109, v121 row_shr:1 row_mask:0xf bank_mask:0xf
	v_fmac_f32_dpp v219, v141, v121 row_shl:15 row_mask:0xf bank_mask:0xf
	v_fmac_f32_e32 v219, v109, v133
	v_cndmask_b32_e64 v104, v145, v149, s[8:9]
	v_mov_b32_e32 v223, v30
	v_fmac_f32_dpp v223, v138, v134 row_shr:2 row_mask:0xf bank_mask:0xf
	v_fmac_f32_dpp v223, v105, v134 row_shl:14 row_mask:0xf bank_mask:0xf
	v_fmac_f32_dpp v223, v138, v118 row_shr:1 row_mask:0xf bank_mask:0xf
	v_fmac_f32_dpp v223, v105, v118 row_shl:15 row_mask:0xf bank_mask:0xf
	v_cndmask_b32_e64 v103, v146, v150, s[8:9]
	v_mov_b32_e32 v224, v31
	v_fmac_f32_dpp v224, v139, v135 row_shr:2 row_mask:0xf bank_mask:0xf
	v_fmac_f32_dpp v224, v104, v135 row_shl:14 row_mask:0xf bank_mask:0xf
	v_fmac_f32_dpp v224, v139, v119 row_shr:1 row_mask:0xf bank_mask:0xf
	v_fmac_f32_dpp v224, v104, v119 row_shl:15 row_mask:0xf bank_mask:0xf
	v_cndmask_b32_e64 v102, v147, v151, s[8:9]
	v_mov_b32_e32 v221, v32
	v_fmac_f32_dpp v221, v140, v136 row_shr:2 row_mask:0xf bank_mask:0xf
	v_fmac_f32_dpp v221, v103, v136 row_shl:14 row_mask:0xf bank_mask:0xf
	v_fmac_f32_dpp v221, v140, v120 row_shr:1 row_mask:0xf bank_mask:0xf
	v_fmac_f32_dpp v221, v103, v120 row_shl:15 row_mask:0xf bank_mask:0xf
	v_mov_b32_e32 v222, v33
	v_fmac_f32_dpp v222, v141, v137 row_shr:2 row_mask:0xf bank_mask:0xf
	v_fmac_f32_dpp v222, v102, v137 row_shl:14 row_mask:0xf bank_mask:0xf
	v_fmac_f32_dpp v222, v141, v121 row_shr:1 row_mask:0xf bank_mask:0xf
	v_fmac_f32_dpp v222, v102, v121 row_shl:15 row_mask:0xf bank_mask:0xf
	v_fmac_f32_e32 v222, v141, v133
	v_cndmask_b32_e64 v102, 0, 1, s[40:41]
	v_fmac_f32_e32 v223, v138, v130
	v_fmac_f32_e32 v224, v139, v131
	v_fmac_f32_e32 v221, v140, v132
	v_cmp_ne_u32_e64 s[12:13], 1, v102
	v_mov_b32_e32 v144, 0
	v_mov_b32_e32 v145, 0
	v_mov_b32_e32 v102, 0
	v_mov_b32_e32 v103, 0
	v_mov_b32_e32 v104, 0
	v_mov_b32_e32 v105, 0
	s_cbranch_vccnz .LBB0_1188
	ds_read_b128 v[142:145], v227 offset:2048
	ds_read_b128 v[102:105], v227 offset:3072
; #define PG8_LAS __attribute__((address_space(3)))
;     __device__ __forceinline__ void operator()(f32x4 (&acc)[2][2][4][2], const Unit& u, int ui, int wr, int wc, int fr_, int fq_) const {
;     ...
; #pragma unroll
;         for (int bj = 0; bj < 2; ++bj)
; #pragma unroll
;             for (int n = 0; n < 2; ++n) { const int ch = bj * 2816 + fbase + 4 * n;
;                 const f32x4 w0 = *(const f32x4*)(cw + ch), w1 = *(const f32x4*)(cw + 5632 + ch), w2 = *(const f32x4*)(cw + 2 * 5632 + ch), bb = *(const f32x4*)(cb + ch);
; #pragma unroll
;                 for (int ai = 0; ai < 2; ++ai) { const int kb = 2 * ai + wr;
;                     f32x4 c62 = (f32x4){0.f, 0.f, 0.f, 0.f}, c63 = c62;
;                     if (kb > 0) { c62 = *(const PG8_LAS f32x4*)(exch + (((kb - 1) * 2 + 0) * 256 + bj * HALF + 32 * wc + 8 * fq + 4 * n)); c63 = *(const PG8_LAS f32x4*)(exch + (((kb - 1) * 2 + 1) * 256 + bj * HALF + 32 * wc + 8 * fq + 4 * n)); }
; #pragma unroll
;                     for (int m = 3; m >= 0; --m) { f32x4 cur = acc[ai][bj][m][n], res;
; #pragma unroll
;                         for (int j = 0; j < 4; ++j) { const float c = cur[j]; const float pv = (m > 0) ? acc[ai][bj][m > 0 ? m - 1 : 0][n][j] : (fr == 15 ? c63[j] : c62[j]); float t1, t2;
;                             asm volatile("s_nop 1\n\tv_mov_b32_dpp %0, %3 row_ror:1 row_mask:0xf bank_mask:0xf\n\tv_mov_b32_dpp %1, %3 row_ror:2 row_mask:0xf bank_mask:0xf\n\t"
;                                          "v_mov_b32_dpp %0, %2 row_shr:1 row_mask:0xf bank_mask:0xf\n\tv_mov_b32_dpp %1, %2 row_shr:2 row_mask:0xf bank_mask:0xf"
;                                          : "=&v"(t1), "=&v"(t2) : "v"(c), "v"(pv));
;                             res[j] = bb[j] + w0[j] * t2 + w1[j] * t1 + w2[j] * c; }
;                         asm volatile("" : "+v"(res[0]), "+v"(res[1]), "+v"(res[2]), "+v"(res[3]));
;                         acc[ai][bj][m][n] = res; } }
.LBB0_1188:
	v_pk_mul_f32 v[46:47], v[46:47], v[188:189] op_sel_hi:[1,0]
	v_pk_mul_f32 v[48:49], v[48:49], v[188:189] op_sel_hi:[1,0]
	v_pk_mul_f32 v[90:91], v[90:91], v[190:191] op_sel_hi:[1,0]
	v_mov_b32_e32 v139, v30
	v_fmac_f32_dpp v139, v126, v134 row_shr:2 row_mask:0xf bank_mask:0xf
	v_fmac_f32_dpp v139, v46, v134 row_shl:14 row_mask:0xf bank_mask:0xf
	v_fmac_f32_dpp v139, v126, v118 row_shr:1 row_mask:0xf bank_mask:0xf
	v_fmac_f32_dpp v139, v46, v118 row_shl:15 row_mask:0xf bank_mask:0xf
	v_fmac_f32_e32 v139, v126, v130
	v_mov_b32_e32 v141, v31
	v_fmac_f32_dpp v141, v127, v135 row_shr:2 row_mask:0xf bank_mask:0xf
	v_fmac_f32_dpp v141, v47, v135 row_shl:14 row_mask:0xf bank_mask:0xf
	v_fmac_f32_dpp v141, v127, v119 row_shr:1 row_mask:0xf bank_mask:0xf
	v_fmac_f32_dpp v141, v47, v119 row_shl:15 row_mask:0xf bank_mask:0xf
	v_fmac_f32_e32 v141, v127, v131
	v_mov_b32_e32 v138, v32
	v_fmac_f32_dpp v138, v128, v136 row_shr:2 row_mask:0xf bank_mask:0xf
	v_fmac_f32_dpp v138, v48, v136 row_shl:14 row_mask:0xf bank_mask:0xf
	v_fmac_f32_dpp v138, v128, v120 row_shr:1 row_mask:0xf bank_mask:0xf
	v_fmac_f32_dpp v138, v48, v120 row_shl:15 row_mask:0xf bank_mask:0xf
	v_fmac_f32_e32 v138, v128, v132
	v_mov_b32_e32 v140, v33
	v_fmac_f32_dpp v140, v129, v137 row_shr:2 row_mask:0xf bank_mask:0xf
	v_fmac_f32_dpp v140, v49, v137 row_shl:14 row_mask:0xf bank_mask:0xf
	v_fmac_f32_dpp v140, v129, v121 row_shr:1 row_mask:0xf bank_mask:0xf
	v_fmac_f32_dpp v140, v49, v121 row_shl:15 row_mask:0xf bank_mask:0xf
	v_fmac_f32_e32 v140, v129, v133
	v_pk_mul_f32 v[92:93], v[92:93], v[190:191] op_sel_hi:[1,0]
	v_mov_b32_e32 v147, v30
	v_fmac_f32_dpp v147, v46, v134 row_shr:2 row_mask:0xf bank_mask:0xf
	v_fmac_f32_dpp v147, v90, v134 row_shl:14 row_mask:0xf bank_mask:0xf
	v_fmac_f32_dpp v147, v46, v118 row_shr:1 row_mask:0xf bank_mask:0xf
	v_fmac_f32_dpp v147, v90, v118 row_shl:15 row_mask:0xf bank_mask:0xf
	v_fmac_f32_e32 v147, v46, v130
	v_pk_mul_f32 v[94:95], v[94:95], v[192:193] op_sel_hi:[1,0]
	v_mov_b32_e32 v149, v31
	v_fmac_f32_dpp v149, v47, v135 row_shr:2 row_mask:0xf bank_mask:0xf
	v_fmac_f32_dpp v149, v91, v135 row_shl:14 row_mask:0xf bank_mask:0xf
	v_fmac_f32_dpp v149, v47, v119 row_shr:1 row_mask:0xf bank_mask:0xf
	v_fmac_f32_dpp v149, v91, v119 row_shl:15 row_mask:0xf bank_mask:0xf
	v_fmac_f32_e32 v149, v47, v131
	v_pk_mul_f32 v[96:97], v[96:97], v[192:193] op_sel_hi:[1,0]
	v_mov_b32_e32 v146, v32
	v_fmac_f32_dpp v146, v48, v136 row_shr:2 row_mask:0xf bank_mask:0xf
	v_fmac_f32_dpp v146, v92, v136 row_shl:14 row_mask:0xf bank_mask:0xf
	v_fmac_f32_dpp v146, v48, v120 row_shr:1 row_mask:0xf bank_mask:0xf
	v_fmac_f32_dpp v146, v92, v120 row_shl:15 row_mask:0xf bank_mask:0xf
	v_fmac_f32_e32 v146, v48, v132
	v_mov_b32_e32 v148, v33
	v_fmac_f32_dpp v148, v49, v137 row_shr:2 row_mask:0xf bank_mask:0xf
	v_fmac_f32_dpp v148, v93, v137 row_shl:14 row_mask:0xf bank_mask:0xf
	v_fmac_f32_dpp v148, v49, v121 row_shr:1 row_mask:0xf bank_mask:0xf
	v_fmac_f32_dpp v148, v93, v121 row_shl:15 row_mask:0xf bank_mask:0xf
	v_fmac_f32_e32 v148, v49, v133
	s_waitcnt lgkmcnt(0)
	v_cndmask_b32_e64 v49, v142, v102, s[8:9]
	v_mov_b32_e32 v151, v30
	v_fmac_f32_dpp v151, v90, v134 row_shr:2 row_mask:0xf bank_mask:0xf
	v_fmac_f32_dpp v151, v94, v134 row_shl:14 row_mask:0xf bank_mask:0xf
	v_fmac_f32_dpp v151, v90, v118 row_shr:1 row_mask:0xf bank_mask:0xf
	v_fmac_f32_dpp v151, v94, v118 row_shl:15 row_mask:0xf bank_mask:0xf
	v_fmac_f32_e32 v151, v90, v130
	v_mov_b32_e32 v215, v31
	v_fmac_f32_dpp v215, v91, v135 row_shr:2 row_mask:0xf bank_mask:0xf
	v_fmac_f32_dpp v215, v95, v135 row_shl:14 row_mask:0xf bank_mask:0xf
	v_fmac_f32_dpp v215, v91, v119 row_shr:1 row_mask:0xf bank_mask:0xf
	v_fmac_f32_dpp v215, v95, v119 row_shl:15 row_mask:0xf bank_mask:0xf
	v_fmac_f32_e32 v215, v91, v131
	v_mov_b32_e32 v150, v32
	v_fmac_f32_dpp v150, v92, v136 row_shr:2 row_mask:0xf bank_mask:0xf
	v_fmac_f32_dpp v150, v96, v136 row_shl:14 row_mask:0xf bank_mask:0xf
	v_fmac_f32_dpp v150, v92, v120 row_shr:1 row_mask:0xf bank_mask:0xf
	v_fmac_f32_dpp v150, v96, v120 row_shl:15 row_mask:0xf bank_mask:0xf
	v_fmac_f32_e32 v150, v92, v132
	v_mov_b32_e32 v155, v33
	v_fmac_f32_dpp v155, v93, v137 row_shr:2 row_mask:0xf bank_mask:0xf
	v_fmac_f32_dpp v155, v97, v137 row_shl:14 row_mask:0xf bank_mask:0xf
	v_fmac_f32_dpp v155, v93, v121 row_shr:1 row_mask:0xf bank_mask:0xf
	v_fmac_f32_dpp v155, v97, v121 row_shl:15 row_mask:0xf bank_mask:0xf
	v_fmac_f32_e32 v155, v93, v133
	v_mov_b32_e32 v229, v30
	v_fmac_f32_dpp v229, v94, v134 row_shr:2 row_mask:0xf bank_mask:0xf
	v_fmac_f32_dpp v229, v49, v134 row_shl:14 row_mask:0xf bank_mask:0xf
	v_fmac_f32_dpp v229, v94, v118 row_shr:1 row_mask:0xf bank_mask:0xf
	v_fmac_f32_dpp v229, v49, v118 row_shl:15 row_mask:0xf bank_mask:0xf
	v_fmac_f32_e32 v229, v94, v130
	v_cndmask_b32_e64 v48, v143, v103, s[8:9]
	v_mov_b32_e32 v134, v229
	v_cndmask_b32_e64 v47, v144, v104, s[8:9]
	v_mov_b32_e32 v130, v31
	v_fmac_f32_dpp v130, v95, v135 row_shr:2 row_mask:0xf bank_mask:0xf
	v_fmac_f32_dpp v130, v48, v135 row_shl:14 row_mask:0xf bank_mask:0xf
	v_fmac_f32_dpp v130, v95, v119 row_shr:1 row_mask:0xf bank_mask:0xf
	v_fmac_f32_dpp v130, v48, v119 row_shl:15 row_mask:0xf bank_mask:0xf
	v_mov_b32_e32 v229, v32
	v_fmac_f32_dpp v229, v96, v136 row_shr:2 row_mask:0xf bank_mask:0xf
	v_fmac_f32_dpp v229, v47, v136 row_shl:14 row_mask:0xf bank_mask:0xf
	v_fmac_f32_dpp v229, v96, v120 row_shr:1 row_mask:0xf bank_mask:0xf
	v_fmac_f32_dpp v229, v47, v120 row_shl:15 row_mask:0xf bank_mask:0xf
	v_fmac_f32_e32 v229, v96, v132
	v_cndmask_b32_e64 v46, v145, v105, s[8:9]
	v_mov_b32_e32 v231, v33
	v_fmac_f32_dpp v231, v97, v137 row_shr:2 row_mask:0xf bank_mask:0xf
	v_fmac_f32_dpp v231, v46, v137 row_shl:14 row_mask:0xf bank_mask:0xf
	v_fmac_f32_dpp v231, v97, v121 row_shr:1 row_mask:0xf bank_mask:0xf
	v_fmac_f32_dpp v231, v46, v121 row_shl:15 row_mask:0xf bank_mask:0xf
	v_fmac_f32_e32 v231, v97, v133
	v_fmac_f32_e32 v130, v95, v131
	v_or_b32_e32 v30, 4, v186
	v_ashrrev_i32_e32 v31, 31, v30
	v_mov_b32_e32 v32, v229
	v_mov_b32_e32 v33, v231
	v_lshlrev_b64 v[30:31], 2, v[30:31]
	v_lshl_add_u64 v[46:47], s[20:21], 0, v[30:31]
	v_lshl_add_u64 v[30:31], s[22:23], 0, v[30:31]
	s_nop 0
	v_mov_b32_e32 v106, 0
	s_and_b64 vcc, exec, s[10:11]
	v_mov_b32_e32 v118, 0
	v_mov_b32_e32 v119, 0
	v_mov_b32_e32 v120, 0
	v_mov_b32_e32 v121, 0
	v_mov_b32_e32 v126, 0
	v_mov_b32_e32 v127, 0
	v_mov_b32_e32 v128, 0
	v_mov_b32_e32 v129, 0
	s_cbranch_vccnz .LBB0_1190
	v_add_u32_e32 v31, 0xfffff810, v227
	v_add_u32_e32 v30, 0xfffffc10, v227
	ds_read_b128 v[118:121], v31
	ds_read_b128 v[126:129], v30

; #define PG8_LAS __attribute__((address_space(3)))
;     __device__ __forceinline__ void operator()(f32x4 (&acc)[2][2][4][2], const Unit& u, int ui, int wr, int wc, int fr_, int fq_) const {
;     ...
; #pragma unroll
;         for (int bj = 0; bj < 2; ++bj)
; #pragma unroll
;             for (int n = 0; n < 2; ++n) { const int ch = bj * 2816 + fbase + 4 * n;
;                 const f32x4 w0 = *(const f32x4*)(cw + ch), w1 = *(const f32x4*)(cw + 5632 + ch), w2 = *(const f32x4*)(cw + 2 * 5632 + ch), bb = *(const f32x4*)(cb + ch);
; #pragma unroll
;                 for (int ai = 0; ai < 2; ++ai) { const int kb = 2 * ai + wr;
;                     f32x4 c62 = (f32x4){0.f, 0.f, 0.f, 0.f}, c63 = c62;
;                     if (kb > 0) { c62 = *(const PG8_LAS f32x4*)(exch + (((kb - 1) * 2 + 0) * 256 + bj * HALF + 32 * wc + 8 * fq + 4 * n)); c63 = *(const PG8_LAS f32x4*)(exch + (((kb - 1) * 2 + 1) * 256 + bj * HALF + 32 * wc + 8 * fq + 4 * n)); }
; #pragma unroll
;                     for (int m = 3; m >= 0; --m) { f32x4 cur = acc[ai][bj][m][n], res;
; #pragma unroll
;                         for (int j = 0; j < 4; ++j) { const float c = cur[j]; const float pv = (m > 0) ? acc[ai][bj][m > 0 ? m - 1 : 0][n][j] : (fr == 15 ? c63[j] : c62[j]); float t1, t2;
;                             asm volatile("s_nop 1\n\tv_mov_b32_dpp %0, %3 row_ror:1 row_mask:0xf bank_mask:0xf\n\tv_mov_b32_dpp %1, %3 row_ror:2 row_mask:0xf bank_mask:0xf\n\t"
;                                          "v_mov_b32_dpp %0, %2 row_shr:1 row_mask:0xf bank_mask:0xf\n\tv_mov_b32_dpp %1, %2 row_shr:2 row_mask:0xf bank_mask:0xf"
;                                          : "=&v"(t1), "=&v"(t2) : "v"(c), "v"(pv));
;                             res[j] = bb[j] + w0[j] * t2 + w1[j] * t1 + w2[j] * c; }
;                         asm volatile("" : "+v"(res[0]), "+v"(res[1]), "+v"(res[2]), "+v"(res[3]));
;                         acc[ai][bj][m][n] = res; } }
.LBB0_1192:
	v_mov_b32_e32 v30, v192
	v_mov_b32_e32 v31, v192
	v_pk_mul_f32 v[30:31], v[68:69], v[30:31]
	v_mov_b32_e32 v189, v188
	v_pk_mul_f32 v[64:65], v[64:65], v[190:191] op_sel_hi:[1,0]
	v_mov_b32_e32 v68, v188
	v_mov_b32_e32 v69, v188
	v_pk_mul_f32 v[56:57], v[56:57], v[68:69]
	v_pk_mul_f32 v[54:55], v[54:55], v[188:189]
	v_mov_b32_e32 v191, v190
	v_pk_mul_f32 v[62:63], v[62:63], v[190:191]
	v_mov_b32_e32 v112, v248
	v_fmac_f32_dpp v112, v114, v234 row_shr:2 row_mask:0xf bank_mask:0xf
	v_fmac_f32_dpp v112, v54, v234 row_shl:14 row_mask:0xf bank_mask:0xf
	v_fmac_f32_dpp v112, v114, v240 row_shr:1 row_mask:0xf bank_mask:0xf
	v_fmac_f32_dpp v112, v54, v240 row_shl:15 row_mask:0xf bank_mask:0xf
	v_fmac_f32_e32 v112, v114, v244
	v_mov_b32_e32 v110, v249
	v_fmac_f32_dpp v110, v115, v235 row_shr:2 row_mask:0xf bank_mask:0xf
	v_fmac_f32_dpp v110, v55, v235 row_shl:14 row_mask:0xf bank_mask:0xf
	v_fmac_f32_dpp v110, v115, v241 row_shr:1 row_mask:0xf bank_mask:0xf
	v_fmac_f32_dpp v110, v55, v241 row_shl:15 row_mask:0xf bank_mask:0xf
	v_fmac_f32_e32 v110, v115, v245
	v_mov_b32_e32 v111, v250
	v_fmac_f32_dpp v111, v116, v236 row_shr:2 row_mask:0xf bank_mask:0xf
	v_fmac_f32_dpp v111, v56, v236 row_shl:14 row_mask:0xf bank_mask:0xf
	v_fmac_f32_dpp v111, v116, v242 row_shr:1 row_mask:0xf bank_mask:0xf
	v_fmac_f32_dpp v111, v56, v242 row_shl:15 row_mask:0xf bank_mask:0xf
	v_fmac_f32_e32 v111, v116, v246
	v_mov_b32_e32 v113, v251
	v_fmac_f32_dpp v113, v117, v237 row_shr:2 row_mask:0xf bank_mask:0xf
	v_fmac_f32_dpp v113, v57, v237 row_shl:14 row_mask:0xf bank_mask:0xf
	v_fmac_f32_dpp v113, v117, v243 row_shr:1 row_mask:0xf bank_mask:0xf
	v_fmac_f32_dpp v113, v57, v243 row_shl:15 row_mask:0xf bank_mask:0xf
	v_fmac_f32_e32 v113, v117, v247
	v_mov_b32_e32 v193, v192
	v_mov_b32_e32 v116, v248
	v_fmac_f32_dpp v116, v54, v234 row_shr:2 row_mask:0xf bank_mask:0xf
	v_fmac_f32_dpp v116, v62, v234 row_shl:14 row_mask:0xf bank_mask:0xf
	v_fmac_f32_dpp v116, v54, v240 row_shr:1 row_mask:0xf bank_mask:0xf
	v_fmac_f32_dpp v116, v62, v240 row_shl:15 row_mask:0xf bank_mask:0xf
	v_fmac_f32_e32 v116, v54, v244
	v_pk_mul_f32 v[66:67], v[66:67], v[192:193]
	v_mov_b32_e32 v114, v249
	v_fmac_f32_dpp v114, v55, v235 row_shr:2 row_mask:0xf bank_mask:0xf
	v_fmac_f32_dpp v114, v63, v235 row_shl:14 row_mask:0xf bank_mask:0xf
	v_fmac_f32_dpp v114, v55, v241 row_shr:1 row_mask:0xf bank_mask:0xf
	v_fmac_f32_dpp v114, v63, v241 row_shl:15 row_mask:0xf bank_mask:0xf
	v_fmac_f32_e32 v114, v55, v245
	s_movk_i32 s0, 0x2000
	v_mov_b32_e32 v115, v250
	v_fmac_f32_dpp v115, v56, v236 row_shr:2 row_mask:0xf bank_mask:0xf
	v_fmac_f32_dpp v115, v64, v236 row_shl:14 row_mask:0xf bank_mask:0xf
	v_fmac_f32_dpp v115, v56, v242 row_shr:1 row_mask:0xf bank_mask:0xf
	v_fmac_f32_dpp v115, v64, v242 row_shl:15 row_mask:0xf bank_mask:0xf
	v_fmac_f32_e32 v115, v56, v246
	v_mov_b32_e32 v117, v251
	v_fmac_f32_dpp v117, v57, v237 row_shr:2 row_mask:0xf bank_mask:0xf
	v_fmac_f32_dpp v117, v65, v237 row_shl:14 row_mask:0xf bank_mask:0xf
	v_fmac_f32_dpp v117, v57, v243 row_shr:1 row_mask:0xf bank_mask:0xf
	v_fmac_f32_dpp v117, v65, v243 row_shl:15 row_mask:0xf bank_mask:0xf
	v_fmac_f32_e32 v117, v57, v247
	s_waitcnt lgkmcnt(0)
; #define PG8_LAS __attribute__((address_space(3)))
;     __device__ __forceinline__ void operator()(f32x4 (&acc)[2][2][4][2], const Unit& u, int ui, int wr, int wc, int fr_, int fq_) const {
;     ...
; #pragma unroll
;         for (int bj = 0; bj < 2; ++bj)
; #pragma unroll
;             for (int n = 0; n < 2; ++n) { const int ch = bj * 2816 + fbase + 4 * n;
;                 const f32x4 w0 = *(const f32x4*)(cw + ch), w1 = *(const f32x4*)(cw + 5632 + ch), w2 = *(const f32x4*)(cw + 2 * 5632 + ch), bb = *(const f32x4*)(cb + ch);
; #pragma unroll
;                 for (int ai = 0; ai < 2; ++ai) { const int kb = 2 * ai + wr;
;                     f32x4 c62 = (f32x4){0.f, 0.f, 0.f, 0.f}, c63 = c62;
;                     if (kb > 0) { c62 = *(const PG8_LAS f32x4*)(exch + (((kb - 1) * 2 + 0) * 256 + bj * HALF + 32 * wc + 8 * fq + 4 * n)); c63 = *(const PG8_LAS f32x4*)(exch + (((kb - 1) * 2 + 1) * 256 + bj * HALF + 32 * wc + 8 * fq + 4 * n)); }
; #pragma unroll
;                     for (int m = 3; m >= 0; --m) { f32x4 cur = acc[ai][bj][m][n], res;
; #pragma unroll
;                         for (int j = 0; j < 4; ++j) { const float c = cur[j]; const float pv = (m > 0) ? acc[ai][bj][m > 0 ? m - 1 : 0][n][j] : (fr == 15 ? c63[j] : c62[j]); float t1, t2;
;                             asm volatile("s_nop 1\n\tv_mov_b32_dpp %0, %3 row_ror:1 row_mask:0xf bank_mask:0xf\n\tv_mov_b32_dpp %1, %3 row_ror:2 row_mask:0xf bank_mask:0xf\n\t"
;                                          "v_mov_b32_dpp %0, %2 row_shr:1 row_mask:0xf bank_mask:0xf\n\tv_mov_b32_dpp %1, %2 row_shr:2 row_mask:0xf bank_mask:0xf"
;                                          : "=&v"(t1), "=&v"(t2) : "v"(c), "v"(pv));
;                             res[j] = bb[j] + w0[j] * t2 + w1[j] * t1 + w2[j] * c; }
;                         asm volatile("" : "+v"(res[0]), "+v"(res[1]), "+v"(res[2]), "+v"(res[3]));
;                         acc[ai][bj][m][n] = res; } }
	v_cndmask_b32_e64 v57, v106, v74, s[8:9]
	v_mov_b32_e32 v120, v248
	v_fmac_f32_dpp v120, v62, v234 row_shr:2 row_mask:0xf bank_mask:0xf
	v_fmac_f32_dpp v120, v66, v234 row_shl:14 row_mask:0xf bank_mask:0xf
	v_fmac_f32_dpp v120, v62, v240 row_shr:1 row_mask:0xf bank_mask:0xf
	v_fmac_f32_dpp v120, v66, v240 row_shl:15 row_mask:0xf bank_mask:0xf
	v_fmac_f32_e32 v120, v62, v244
	v_mov_b32_e32 v118, v249
	v_fmac_f32_dpp v118, v63, v235 row_shr:2 row_mask:0xf bank_mask:0xf
	v_fmac_f32_dpp v118, v67, v235 row_shl:14 row_mask:0xf bank_mask:0xf
	v_fmac_f32_dpp v118, v63, v241 row_shr:1 row_mask:0xf bank_mask:0xf
	v_fmac_f32_dpp v118, v67, v241 row_shl:15 row_mask:0xf bank_mask:0xf
	v_fmac_f32_e32 v118, v63, v245
	v_mov_b32_e32 v119, v250
	v_fmac_f32_dpp v119, v64, v236 row_shr:2 row_mask:0xf bank_mask:0xf
	v_fmac_f32_dpp v119, v30, v236 row_shl:14 row_mask:0xf bank_mask:0xf
	v_fmac_f32_dpp v119, v64, v242 row_shr:1 row_mask:0xf bank_mask:0xf
	v_fmac_f32_dpp v119, v30, v242 row_shl:15 row_mask:0xf bank_mask:0xf
	v_fmac_f32_e32 v119, v64, v246
	v_mov_b32_e32 v121, v251
	v_fmac_f32_dpp v121, v65, v237 row_shr:2 row_mask:0xf bank_mask:0xf
	v_fmac_f32_dpp v121, v31, v237 row_shl:14 row_mask:0xf bank_mask:0xf
	v_fmac_f32_dpp v121, v65, v243 row_shr:1 row_mask:0xf bank_mask:0xf
	v_fmac_f32_dpp v121, v31, v243 row_shl:15 row_mask:0xf bank_mask:0xf
	v_fmac_f32_e32 v121, v65, v247
	v_cndmask_b32_e64 v56, v107, v75, s[8:9]
	v_mov_b32_e32 v106, v248
	v_fmac_f32_dpp v106, v66, v234 row_shr:2 row_mask:0xf bank_mask:0xf
	v_fmac_f32_dpp v106, v57, v234 row_shl:14 row_mask:0xf bank_mask:0xf
	v_fmac_f32_dpp v106, v66, v240 row_shr:1 row_mask:0xf bank_mask:0xf
	v_fmac_f32_dpp v106, v57, v240 row_shl:15 row_mask:0xf bank_mask:0xf
	v_cndmask_b32_e64 v55, v108, v76, s[8:9]
	v_mov_b32_e32 v102, v249
	v_fmac_f32_dpp v102, v67, v235 row_shr:2 row_mask:0xf bank_mask:0xf
	v_fmac_f32_dpp v102, v56, v235 row_shl:14 row_mask:0xf bank_mask:0xf
	v_fmac_f32_dpp v102, v67, v241 row_shr:1 row_mask:0xf bank_mask:0xf
	v_fmac_f32_dpp v102, v56, v241 row_shl:15 row_mask:0xf bank_mask:0xf
	v_mov_b32_e32 v48, v250
	v_fmac_f32_dpp v48, v30, v236 row_shr:2 row_mask:0xf bank_mask:0xf
	v_fmac_f32_dpp v48, v55, v236 row_shl:14 row_mask:0xf bank_mask:0xf
	v_fmac_f32_dpp v48, v30, v242 row_shr:1 row_mask:0xf bank_mask:0xf
	v_fmac_f32_dpp v48, v55, v242 row_shl:15 row_mask:0xf bank_mask:0xf
	v_fmac_f32_e32 v48, v30, v246
	v_cndmask_b32_e64 v54, v109, v77, s[8:9]
	v_mov_b32_e32 v49, v251
	v_fmac_f32_dpp v49, v31, v237 row_shr:2 row_mask:0xf bank_mask:0xf
	v_fmac_f32_dpp v49, v54, v237 row_shl:14 row_mask:0xf bank_mask:0xf
	v_fmac_f32_dpp v49, v31, v243 row_shr:1 row_mask:0xf bank_mask:0xf
	v_fmac_f32_dpp v49, v54, v243 row_shl:15 row_mask:0xf bank_mask:0xf
	v_fmac_f32_e32 v49, v31, v247
	v_fmac_f32_e32 v106, v66, v244
	v_add_co_u32_e32 v30, vcc, s0, v204
	s_nop 0
	v_addc_co_u32_e32 v31, vcc, 0, v205, vcc
	v_add_co_u32_e32 v46, vcc, s0, v202
	v_fmac_f32_e32 v102, v67, v245
	s_nop 0
	v_addc_co_u32_e32 v47, vcc, 0, v203, vcc
	v_add_co_u32_e32 v54, vcc, 0x2000, v200
	global_load_dwordx4 v[62:65], v[30:31], off offset:3072
	global_load_dwordx4 v[66:69], v[46:47], off offset:3072
	global_load_dwordx4 v[234:237], v[30:31], off offset:3088
	global_load_dwordx4 v[240:243], v[46:47], off offset:3088
	v_addc_co_u32_e32 v55, vcc, 0, v201, vcc
	global_load_dwordx4 v[74:77], v[54:55], off offset:3072
	global_load_dwordx4 v[244:247], v[54:55], off offset:3088
	v_add_co_u32_e32 v54, vcc, 0x2000, v198
	v_mov_b32_e32 v78, 0
	s_nop 0
	v_addc_co_u32_e32 v55, vcc, 0, v199, vcc
	global_load_dwordx4 v[248:251], v[54:55], off offset:3088
	global_load_dwordx4 v[54:57], v[54:55], off offset:3072
	s_and_b64 vcc, exec, s[10:11]
	v_mov_b32_e32 v90, 0
	v_mov_b32_e32 v91, 0
	v_mov_b32_e32 v92, 0
	v_mov_b32_e32 v93, 0
	v_mov_b32_e32 v94, 0
	v_mov_b32_e32 v95, 0
	v_mov_b32_e32 v96, 0
	v_mov_b32_e32 v97, 0
	s_cbranch_vccnz .LBB0_1194
	v_add_u32_e32 v80, s43, v228
	v_add_u32_e32 v79, s30, v228
	ds_read_b128 v[90:93], v80
	ds_read_b128 v[94:97], v79

; #define PG8_LAS __attribute__((address_space(3)))
;     __device__ __forceinline__ void operator()(f32x4 (&acc)[2][2][4][2], const Unit& u, int ui, int wr, int wc, int fr_, int fq_) const {
;     ...
; #pragma unroll
;         for (int bj = 0; bj < 2; ++bj)
; #pragma unroll
;             for (int n = 0; n < 2; ++n) { const int ch = bj * 2816 + fbase + 4 * n;
;                 const f32x4 w0 = *(const f32x4*)(cw + ch), w1 = *(const f32x4*)(cw + 5632 + ch), w2 = *(const f32x4*)(cw + 2 * 5632 + ch), bb = *(const f32x4*)(cb + ch);
; #pragma unroll
;                 for (int ai = 0; ai < 2; ++ai) { const int kb = 2 * ai + wr;
;                     f32x4 c62 = (f32x4){0.f, 0.f, 0.f, 0.f}, c63 = c62;
;                     if (kb > 0) { c62 = *(const PG8_LAS f32x4*)(exch + (((kb - 1) * 2 + 0) * 256 + bj * HALF + 32 * wc + 8 * fq + 4 * n)); c63 = *(const PG8_LAS f32x4*)(exch + (((kb - 1) * 2 + 1) * 256 + bj * HALF + 32 * wc + 8 * fq + 4 * n)); }
; #pragma unroll
;                     for (int m = 3; m >= 0; --m) { f32x4 cur = acc[ai][bj][m][n], res;
; #pragma unroll
;                         for (int j = 0; j < 4; ++j) { const float c = cur[j]; const float pv = (m > 0) ? acc[ai][bj][m > 0 ? m - 1 : 0][n][j] : (fr == 15 ? c63[j] : c62[j]); float t1, t2;
;                             asm volatile("s_nop 1\n\tv_mov_b32_dpp %0, %3 row_ror:1 row_mask:0xf bank_mask:0xf\n\tv_mov_b32_dpp %1, %3 row_ror:2 row_mask:0xf bank_mask:0xf\n\t"
;                                          "v_mov_b32_dpp %0, %2 row_shr:1 row_mask:0xf bank_mask:0xf\n\tv_mov_b32_dpp %1, %2 row_shr:2 row_mask:0xf bank_mask:0xf"
;                                          : "=&v"(t1), "=&v"(t2) : "v"(c), "v"(pv));
;                             res[j] = bb[j] + w0[j] * t2 + w1[j] * t1 + w2[j] * c; }
;                         asm volatile("" : "+v"(res[0]), "+v"(res[1]), "+v"(res[2]), "+v"(res[3]));
;                         acc[ai][bj][m][n] = res; } }
.LBB0_1196:
	v_pk_mul_f32 v[36:37], v[36:37], v[192:193] op_sel_hi:[1,0]
	v_pk_mul_f32 v[28:29], v[28:29], v[190:191] op_sel_hi:[1,0]
	v_pk_mul_f32 v[24:25], v[24:25], v[188:189] op_sel_hi:[1,0]
	v_pk_mul_f32 v[22:23], v[22:23], v[188:189]
	v_pk_mul_f32 v[26:27], v[26:27], v[190:191]
	v_pk_mul_f32 v[34:35], v[34:35], v[192:193]
	v_mov_b32_e32 v87, v54
	v_fmac_f32_dpp v87, v82, v62 row_shr:2 row_mask:0xf bank_mask:0xf
	v_fmac_f32_dpp v87, v22, v62 row_shl:14 row_mask:0xf bank_mask:0xf
	v_fmac_f32_dpp v87, v82, v66 row_shr:1 row_mask:0xf bank_mask:0xf
	v_fmac_f32_dpp v87, v22, v66 row_shl:15 row_mask:0xf bank_mask:0xf
	v_fmac_f32_e32 v87, v82, v74
	v_mov_b32_e32 v86, v55
	v_fmac_f32_dpp v86, v83, v63 row_shr:2 row_mask:0xf bank_mask:0xf
	v_fmac_f32_dpp v86, v23, v63 row_shl:14 row_mask:0xf bank_mask:0xf
	v_fmac_f32_dpp v86, v83, v67 row_shr:1 row_mask:0xf bank_mask:0xf
	v_fmac_f32_dpp v86, v23, v67 row_shl:15 row_mask:0xf bank_mask:0xf
	v_fmac_f32_e32 v86, v83, v75
	v_mov_b32_e32 v82, v56
	v_fmac_f32_dpp v82, v84, v64 row_shr:2 row_mask:0xf bank_mask:0xf
	v_fmac_f32_dpp v82, v24, v64 row_shl:14 row_mask:0xf bank_mask:0xf
	v_fmac_f32_dpp v82, v84, v68 row_shr:1 row_mask:0xf bank_mask:0xf
	v_fmac_f32_dpp v82, v24, v68 row_shl:15 row_mask:0xf bank_mask:0xf
	v_fmac_f32_e32 v82, v84, v76
	v_mov_b32_e32 v83, v57
	v_fmac_f32_dpp v83, v85, v65 row_shr:2 row_mask:0xf bank_mask:0xf
	v_fmac_f32_dpp v83, v25, v65 row_shl:14 row_mask:0xf bank_mask:0xf
	v_fmac_f32_dpp v83, v85, v69 row_shr:1 row_mask:0xf bank_mask:0xf
	v_fmac_f32_dpp v83, v25, v69 row_shl:15 row_mask:0xf bank_mask:0xf
	v_fmac_f32_e32 v83, v85, v77
	v_mov_b32_e32 v44, 0
	v_mov_b32_e32 v89, v54
	v_fmac_f32_dpp v89, v22, v62 row_shr:2 row_mask:0xf bank_mask:0xf
	v_fmac_f32_dpp v89, v26, v62 row_shl:14 row_mask:0xf bank_mask:0xf
	v_fmac_f32_dpp v89, v22, v66 row_shr:1 row_mask:0xf bank_mask:0xf
	v_fmac_f32_dpp v89, v26, v66 row_shl:15 row_mask:0xf bank_mask:0xf
	v_fmac_f32_e32 v89, v22, v74
	v_mov_b32_e32 v45, 0
	v_mov_b32_e32 v88, v55
	v_fmac_f32_dpp v88, v23, v63 row_shr:2 row_mask:0xf bank_mask:0xf
	v_fmac_f32_dpp v88, v27, v63 row_shl:14 row_mask:0xf bank_mask:0xf
	v_fmac_f32_dpp v88, v23, v67 row_shr:1 row_mask:0xf bank_mask:0xf
	v_fmac_f32_dpp v88, v27, v67 row_shl:15 row_mask:0xf bank_mask:0xf
	v_fmac_f32_e32 v88, v23, v75
	v_mov_b32_e32 v42, 0
	v_mov_b32_e32 v84, v56
	v_fmac_f32_dpp v84, v24, v64 row_shr:2 row_mask:0xf bank_mask:0xf
	v_fmac_f32_dpp v84, v28, v64 row_shl:14 row_mask:0xf bank_mask:0xf
	v_fmac_f32_dpp v84, v24, v68 row_shr:1 row_mask:0xf bank_mask:0xf
	v_fmac_f32_dpp v84, v28, v68 row_shl:15 row_mask:0xf bank_mask:0xf
	v_fmac_f32_e32 v84, v24, v76
	v_mov_b32_e32 v85, v57
	v_fmac_f32_dpp v85, v25, v65 row_shr:2 row_mask:0xf bank_mask:0xf
	v_fmac_f32_dpp v85, v29, v65 row_shl:14 row_mask:0xf bank_mask:0xf
	v_fmac_f32_dpp v85, v25, v69 row_shr:1 row_mask:0xf bank_mask:0xf
	v_fmac_f32_dpp v85, v29, v69 row_shl:15 row_mask:0xf bank_mask:0xf
	v_fmac_f32_e32 v85, v25, v77
	s_waitcnt lgkmcnt(0)
	v_cndmask_b32_e64 v25, v78, v38, s[8:9]
	v_mov_b32_e32 v93, v54
	v_fmac_f32_dpp v93, v26, v62 row_shr:2 row_mask:0xf bank_mask:0xf
	v_fmac_f32_dpp v93, v34, v62 row_shl:14 row_mask:0xf bank_mask:0xf
	v_fmac_f32_dpp v93, v26, v66 row_shr:1 row_mask:0xf bank_mask:0xf
	v_fmac_f32_dpp v93, v34, v66 row_shl:15 row_mask:0xf bank_mask:0xf
	v_fmac_f32_e32 v93, v26, v74
	v_mov_b32_e32 v92, v55
	v_fmac_f32_dpp v92, v27, v63 row_shr:2 row_mask:0xf bank_mask:0xf
	v_fmac_f32_dpp v92, v35, v63 row_shl:14 row_mask:0xf bank_mask:0xf
	v_fmac_f32_dpp v92, v27, v67 row_shr:1 row_mask:0xf bank_mask:0xf
	v_fmac_f32_dpp v92, v35, v67 row_shl:15 row_mask:0xf bank_mask:0xf
	v_fmac_f32_e32 v92, v27, v75
	v_mov_b32_e32 v90, v56
	v_fmac_f32_dpp v90, v28, v64 row_shr:2 row_mask:0xf bank_mask:0xf
	v_fmac_f32_dpp v90, v36, v64 row_shl:14 row_mask:0xf bank_mask:0xf
	v_fmac_f32_dpp v90, v28, v68 row_shr:1 row_mask:0xf bank_mask:0xf
	v_fmac_f32_dpp v90, v36, v68 row_shl:15 row_mask:0xf bank_mask:0xf
	v_fmac_f32_e32 v90, v28, v76
	v_mov_b32_e32 v91, v57
	v_fmac_f32_dpp v91, v29, v65 row_shr:2 row_mask:0xf bank_mask:0xf
	v_fmac_f32_dpp v91, v37, v65 row_shl:14 row_mask:0xf bank_mask:0xf
	v_fmac_f32_dpp v91, v29, v69 row_shr:1 row_mask:0xf bank_mask:0xf
	v_fmac_f32_dpp v91, v37, v69 row_shl:15 row_mask:0xf bank_mask:0xf
	v_fmac_f32_e32 v91, v29, v77
	v_cndmask_b32_e64 v24, v79, v39, s[8:9]
	v_mov_b32_e32 v78, v54
	v_fmac_f32_dpp v78, v34, v62 row_shr:2 row_mask:0xf bank_mask:0xf
	v_fmac_f32_dpp v78, v25, v62 row_shl:14 row_mask:0xf bank_mask:0xf
	v_fmac_f32_dpp v78, v34, v66 row_shr:1 row_mask:0xf bank_mask:0xf
	v_fmac_f32_dpp v78, v25, v66 row_shl:15 row_mask:0xf bank_mask:0xf
	v_mov_b32_e32 v229, v55
	v_fmac_f32_dpp v229, v35, v63 row_shr:2 row_mask:0xf bank_mask:0xf
	v_fmac_f32_dpp v229, v24, v63 row_shl:14 row_mask:0xf bank_mask:0xf
	v_fmac_f32_dpp v229, v35, v67 row_shr:1 row_mask:0xf bank_mask:0xf
	v_fmac_f32_dpp v229, v24, v67 row_shl:15 row_mask:0xf bank_mask:0xf
	v_fmac_f32_e32 v229, v35, v75
	v_cndmask_b32_e64 v23, v80, v40, s[8:9]
	v_cndmask_b32_e64 v22, v81, v41, s[8:9]
	v_mov_b32_e32 v54, v56
	v_fmac_f32_dpp v54, v36, v64 row_shr:2 row_mask:0xf bank_mask:0xf
	v_fmac_f32_dpp v54, v23, v64 row_shl:14 row_mask:0xf bank_mask:0xf
	v_fmac_f32_dpp v54, v36, v68 row_shr:1 row_mask:0xf bank_mask:0xf
	v_fmac_f32_dpp v54, v23, v68 row_shl:15 row_mask:0xf bank_mask:0xf
	v_mov_b32_e32 v231, v57
	v_fmac_f32_dpp v231, v37, v65 row_shr:2 row_mask:0xf bank_mask:0xf
	v_fmac_f32_dpp v231, v22, v65 row_shl:14 row_mask:0xf bank_mask:0xf
	v_fmac_f32_dpp v231, v37, v69 row_shr:1 row_mask:0xf bank_mask:0xf
	v_fmac_f32_dpp v231, v22, v69 row_shl:15 row_mask:0xf bank_mask:0xf
	v_fmac_f32_e32 v231, v37, v77
	v_fmac_f32_e32 v78, v34, v74
	v_mov_b32_e32 v55, v229
	v_fmac_f32_e32 v54, v36, v76
	v_mov_b32_e32 v57, v231
	s_waitcnt vmcnt(0)
	v_mov_b32_e32 v46, 0
	v_mov_b32_e32 v47, 0
	s_and_b64 vcc, exec, s[10:11]
	v_mov_b32_e32 v62, 0
	v_mov_b32_e32 v63, 0
	v_mov_b32_e32 v64, 0
	v_mov_b32_e32 v65, 0
	s_cbranch_vccnz .LBB0_1198
	v_add_u32_e32 v31, 0xfffffa10, v227
	v_add_u32_e32 v30, 0xfffffe10, v227
	ds_read_b128 v[44:47], v31
	ds_read_b128 v[62:65], v30
; #define PG8_LAS __attribute__((address_space(3)))
;     __device__ __forceinline__ void operator()(f32x4 (&acc)[2][2][4][2], const Unit& u, int ui, int wr, int wc, int fr_, int fq_) const {
;     ...
; #pragma unroll
;         for (int bj = 0; bj < 2; ++bj)
; #pragma unroll
;             for (int n = 0; n < 2; ++n) { const int ch = bj * 2816 + fbase + 4 * n;
;                 const f32x4 w0 = *(const f32x4*)(cw + ch), w1 = *(const f32x4*)(cw + 5632 + ch), w2 = *(const f32x4*)(cw + 2 * 5632 + ch), bb = *(const f32x4*)(cb + ch);
; #pragma unroll
;                 for (int ai = 0; ai < 2; ++ai) { const int kb = 2 * ai + wr;
;                     f32x4 c62 = (f32x4){0.f, 0.f, 0.f, 0.f}, c63 = c62;
;                     if (kb > 0) { c62 = *(const PG8_LAS f32x4*)(exch + (((kb - 1) * 2 + 0) * 256 + bj * HALF + 32 * wc + 8 * fq + 4 * n)); c63 = *(const PG8_LAS f32x4*)(exch + (((kb - 1) * 2 + 1) * 256 + bj * HALF + 32 * wc + 8 * fq + 4 * n)); }
; #pragma unroll
;                     for (int m = 3; m >= 0; --m) { f32x4 cur = acc[ai][bj][m][n], res;
; #pragma unroll
;                         for (int j = 0; j < 4; ++j) { const float c = cur[j]; const float pv = (m > 0) ? acc[ai][bj][m > 0 ? m - 1 : 0][n][j] : (fr == 15 ? c63[j] : c62[j]); float t1, t2;
;                             asm volatile("s_nop 1\n\tv_mov_b32_dpp %0, %3 row_ror:1 row_mask:0xf bank_mask:0xf\n\tv_mov_b32_dpp %1, %3 row_ror:2 row_mask:0xf bank_mask:0xf\n\t"
;                                          "v_mov_b32_dpp %0, %2 row_shr:1 row_mask:0xf bank_mask:0xf\n\tv_mov_b32_dpp %1, %2 row_shr:2 row_mask:0xf bank_mask:0xf"
;                                          : "=&v"(t1), "=&v"(t2) : "v"(c), "v"(pv));
;                             res[j] = bb[j] + w0[j] * t2 + w1[j] * t1 + w2[j] * c; }
;                         asm volatile("" : "+v"(res[0]), "+v"(res[1]), "+v"(res[2]), "+v"(res[3]));
;                         acc[ai][bj][m][n] = res; } }
.LBB0_1198:
	v_pk_mul_f32 v[76:77], v[18:19], v[194:195]
	v_pk_mul_f32 v[74:75], v[20:21], v[194:195] op_sel_hi:[1,0]
	v_pk_mul_f32 v[16:17], v[16:17], v[196:197] op_sel_hi:[1,0]
	v_pk_mul_f32 v[14:15], v[14:15], v[196:197]
	s_and_b64 vcc, exec, s[12:13]
	s_waitcnt vmcnt(0)
	v_mov_b32_e32 v20, v248
	v_fmac_f32_dpp v20, v70, v234 row_shr:2 row_mask:0xf bank_mask:0xf
	v_fmac_f32_dpp v20, v14, v234 row_shl:14 row_mask:0xf bank_mask:0xf
	v_fmac_f32_dpp v20, v70, v240 row_shr:1 row_mask:0xf bank_mask:0xf
	v_fmac_f32_dpp v20, v14, v240 row_shl:15 row_mask:0xf bank_mask:0xf
	v_fmac_f32_e32 v20, v70, v244
	v_mov_b32_e32 v18, v249
	v_fmac_f32_dpp v18, v71, v235 row_shr:2 row_mask:0xf bank_mask:0xf
	v_fmac_f32_dpp v18, v15, v235 row_shl:14 row_mask:0xf bank_mask:0xf
	v_fmac_f32_dpp v18, v71, v241 row_shr:1 row_mask:0xf bank_mask:0xf
	v_fmac_f32_dpp v18, v15, v241 row_shl:15 row_mask:0xf bank_mask:0xf
	v_fmac_f32_e32 v18, v71, v245
	v_mov_b32_e32 v19, v250
	v_fmac_f32_dpp v19, v72, v236 row_shr:2 row_mask:0xf bank_mask:0xf
	v_fmac_f32_dpp v19, v16, v236 row_shl:14 row_mask:0xf bank_mask:0xf
	v_fmac_f32_dpp v19, v72, v242 row_shr:1 row_mask:0xf bank_mask:0xf
	v_fmac_f32_dpp v19, v16, v242 row_shl:15 row_mask:0xf bank_mask:0xf
	v_fmac_f32_e32 v19, v72, v246
	v_mov_b32_e32 v21, v251
	v_fmac_f32_dpp v21, v73, v237 row_shr:2 row_mask:0xf bank_mask:0xf
	v_fmac_f32_dpp v21, v17, v237 row_shl:14 row_mask:0xf bank_mask:0xf
	v_fmac_f32_dpp v21, v73, v243 row_shr:1 row_mask:0xf bank_mask:0xf
	v_fmac_f32_dpp v21, v17, v243 row_shl:15 row_mask:0xf bank_mask:0xf
	v_fmac_f32_e32 v21, v73, v247
	s_nop 0
	v_mov_b32_e32 v56, v248
	v_fmac_f32_dpp v56, v14, v234 row_shr:2 row_mask:0xf bank_mask:0xf
	v_fmac_f32_dpp v56, v76, v234 row_shl:14 row_mask:0xf bank_mask:0xf
	v_fmac_f32_dpp v56, v14, v240 row_shr:1 row_mask:0xf bank_mask:0xf
	v_fmac_f32_dpp v56, v76, v240 row_shl:15 row_mask:0xf bank_mask:0xf
	v_fmac_f32_e32 v56, v14, v244
	s_nop 0
	v_mov_b32_e32 v30, v249
	v_fmac_f32_dpp v30, v15, v235 row_shr:2 row_mask:0xf bank_mask:0xf
	v_fmac_f32_dpp v30, v77, v235 row_shl:14 row_mask:0xf bank_mask:0xf
	v_fmac_f32_dpp v30, v15, v241 row_shr:1 row_mask:0xf bank_mask:0xf
	v_fmac_f32_dpp v30, v77, v241 row_shl:15 row_mask:0xf bank_mask:0xf
	v_fmac_f32_e32 v30, v15, v245
	s_nop 0
	v_mov_b32_e32 v31, v250
	v_fmac_f32_dpp v31, v16, v236 row_shr:2 row_mask:0xf bank_mask:0xf
	v_fmac_f32_dpp v31, v74, v236 row_shl:14 row_mask:0xf bank_mask:0xf
	v_fmac_f32_dpp v31, v16, v242 row_shr:1 row_mask:0xf bank_mask:0xf
	v_fmac_f32_dpp v31, v74, v242 row_shl:15 row_mask:0xf bank_mask:0xf
	v_fmac_f32_e32 v31, v16, v246
	v_mov_b32_e32 v66, v251
	v_fmac_f32_dpp v66, v17, v237 row_shr:2 row_mask:0xf bank_mask:0xf
	v_fmac_f32_dpp v66, v75, v237 row_shl:14 row_mask:0xf bank_mask:0xf
	v_fmac_f32_dpp v66, v17, v243 row_shr:1 row_mask:0xf bank_mask:0xf
	v_fmac_f32_dpp v66, v75, v243 row_shl:15 row_mask:0xf bank_mask:0xf
	v_fmac_f32_e32 v66, v17, v247
	s_waitcnt lgkmcnt(0)
	v_cndmask_b32_e64 v17, v44, v62, s[8:9]
	v_mov_b32_e32 v69, v248
	v_fmac_f32_dpp v69, v76, v234 row_shr:2 row_mask:0xf bank_mask:0xf
	v_fmac_f32_dpp v69, v58, v234 row_shl:14 row_mask:0xf bank_mask:0xf
	v_fmac_f32_dpp v69, v76, v240 row_shr:1 row_mask:0xf bank_mask:0xf
	v_fmac_f32_dpp v69, v58, v240 row_shl:15 row_mask:0xf bank_mask:0xf
	v_fmac_f32_e32 v69, v76, v244
	v_mov_b32_e32 v67, v249
	v_fmac_f32_dpp v67, v77, v235 row_shr:2 row_mask:0xf bank_mask:0xf
	v_fmac_f32_dpp v67, v59, v235 row_shl:14 row_mask:0xf bank_mask:0xf
	v_fmac_f32_dpp v67, v77, v241 row_shr:1 row_mask:0xf bank_mask:0xf
	v_fmac_f32_dpp v67, v59, v241 row_shl:15 row_mask:0xf bank_mask:0xf
	v_fmac_f32_e32 v67, v77, v245
	v_mov_b32_e32 v68, v250
	v_fmac_f32_dpp v68, v74, v236 row_shr:2 row_mask:0xf bank_mask:0xf
	v_fmac_f32_dpp v68, v60, v236 row_shl:14 row_mask:0xf bank_mask:0xf
	v_fmac_f32_dpp v68, v74, v242 row_shr:1 row_mask:0xf bank_mask:0xf
	v_fmac_f32_dpp v68, v60, v242 row_shl:15 row_mask:0xf bank_mask:0xf
	v_fmac_f32_e32 v68, v74, v246
	v_mov_b32_e32 v70, v251
	v_fmac_f32_dpp v70, v75, v237 row_shr:2 row_mask:0xf bank_mask:0xf
	v_fmac_f32_dpp v70, v61, v237 row_shl:14 row_mask:0xf bank_mask:0xf
	v_fmac_f32_dpp v70, v75, v243 row_shr:1 row_mask:0xf bank_mask:0xf
	v_fmac_f32_dpp v70, v61, v243 row_shl:15 row_mask:0xf bank_mask:0xf
	v_fmac_f32_e32 v70, v75, v247
	v_cndmask_b32_e64 v16, v45, v63, s[8:9]
	v_mov_b32_e32 v62, v248
	v_fmac_f32_dpp v62, v58, v234 row_shr:2 row_mask:0xf bank_mask:0xf
	v_fmac_f32_dpp v62, v17, v234 row_shl:14 row_mask:0xf bank_mask:0xf
	v_fmac_f32_dpp v62, v58, v240 row_shr:1 row_mask:0xf bank_mask:0xf
	v_fmac_f32_dpp v62, v17, v240 row_shl:15 row_mask:0xf bank_mask:0xf
	v_fmac_f32_e32 v62, v58, v244
	v_cndmask_b32_e64 v15, v46, v64, s[8:9]
	v_mov_b32_e32 v58, v249
	v_fmac_f32_dpp v58, v59, v235 row_shr:2 row_mask:0xf bank_mask:0xf
	v_fmac_f32_dpp v58, v16, v235 row_shl:14 row_mask:0xf bank_mask:0xf
	v_fmac_f32_dpp v58, v59, v241 row_shr:1 row_mask:0xf bank_mask:0xf
	v_fmac_f32_dpp v58, v16, v241 row_shl:15 row_mask:0xf bank_mask:0xf
	v_fmac_f32_e32 v58, v59, v245
	v_cndmask_b32_e64 v14, v47, v65, s[8:9]
	v_mov_b32_e32 v59, v250
	v_fmac_f32_dpp v59, v60, v236 row_shr:2 row_mask:0xf bank_mask:0xf
	v_fmac_f32_dpp v59, v15, v236 row_shl:14 row_mask:0xf bank_mask:0xf
	v_fmac_f32_dpp v59, v60, v242 row_shr:1 row_mask:0xf bank_mask:0xf
	v_fmac_f32_dpp v59, v15, v242 row_shl:15 row_mask:0xf bank_mask:0xf
	v_fmac_f32_e32 v59, v60, v246
	v_mov_b32_e32 v43, 0
	v_mov_b32_e32 v60, v251
	v_fmac_f32_dpp v60, v61, v237 row_shr:2 row_mask:0xf bank_mask:0xf
	v_fmac_f32_dpp v60, v14, v237 row_shl:14 row_mask:0xf bank_mask:0xf
	v_fmac_f32_dpp v60, v61, v243 row_shr:1 row_mask:0xf bank_mask:0xf
	v_fmac_f32_dpp v60, v14, v243 row_shl:15 row_mask:0xf bank_mask:0xf
	v_fmac_f32_e32 v60, v61, v247
	v_mov_b32_e32 v44, 0
	v_mov_b32_e32 v45, 0
	v_mov_b32_e32 v14, 0
	v_mov_b32_e32 v15, 0
	v_mov_b32_e32 v16, 0
	v_mov_b32_e32 v17, 0
	s_cbranch_vccnz .LBB0_1200
	ds_read_b128 v[42:45], v227 offset:2576
	ds_read_b128 v[14:17], v227 offset:3600
; #define PG8_LAS __attribute__((address_space(3)))
;     __device__ __forceinline__ void operator()(f32x4 (&acc)[2][2][4][2], const Unit& u, int ui, int wr, int wc, int fr_, int fq_) const {
;     ...
; #pragma unroll
;         for (int bj = 0; bj < 2; ++bj)
; #pragma unroll
;             for (int n = 0; n < 2; ++n) { const int ch = bj * 2816 + fbase + 4 * n;
;                 const f32x4 w0 = *(const f32x4*)(cw + ch), w1 = *(const f32x4*)(cw + 5632 + ch), w2 = *(const f32x4*)(cw + 2 * 5632 + ch), bb = *(const f32x4*)(cb + ch);
; #pragma unroll
;                 for (int ai = 0; ai < 2; ++ai) { const int kb = 2 * ai + wr;
;                     f32x4 c62 = (f32x4){0.f, 0.f, 0.f, 0.f}, c63 = c62;
;                     if (kb > 0) { c62 = *(const PG8_LAS f32x4*)(exch + (((kb - 1) * 2 + 0) * 256 + bj * HALF + 32 * wc + 8 * fq + 4 * n)); c63 = *(const PG8_LAS f32x4*)(exch + (((kb - 1) * 2 + 1) * 256 + bj * HALF + 32 * wc + 8 * fq + 4 * n)); }
; #pragma unroll
;                     for (int m = 3; m >= 0; --m) { f32x4 cur = acc[ai][bj][m][n], res;
; #pragma unroll
;                         for (int j = 0; j < 4; ++j) { const float c = cur[j]; const float pv = (m > 0) ? acc[ai][bj][m > 0 ? m - 1 : 0][n][j] : (fr == 15 ? c63[j] : c62[j]); float t1, t2;
;                             asm volatile("s_nop 1\n\tv_mov_b32_dpp %0, %3 row_ror:1 row_mask:0xf bank_mask:0xf\n\tv_mov_b32_dpp %1, %3 row_ror:2 row_mask:0xf bank_mask:0xf\n\t"
;                                          "v_mov_b32_dpp %0, %2 row_shr:1 row_mask:0xf bank_mask:0xf\n\tv_mov_b32_dpp %1, %2 row_shr:2 row_mask:0xf bank_mask:0xf"
;                                          : "=&v"(t1), "=&v"(t2) : "v"(c), "v"(pv));
;                             res[j] = bb[j] + w0[j] * t2 + w1[j] * t1 + w2[j] * c; }
;                         asm volatile("" : "+v"(res[0]), "+v"(res[1]), "+v"(res[2]), "+v"(res[3]));
;                         acc[ai][bj][m][n] = res; } }
.LBB0_1200:
	v_pk_mul_f32 v[76:77], v[6:7], v[190:191]
	v_pk_mul_f32 v[72:73], v[10:11], v[192:193]
	v_pk_mul_f32 v[4:5], v[4:5], v[188:189] op_sel_hi:[1,0]
	v_pk_mul_f32 v[2:3], v[2:3], v[188:189]
	v_pk_mul_f32 v[74:75], v[8:9], v[190:191] op_sel_hi:[1,0]
	v_mov_b32_e32 v7, v248
	v_fmac_f32_dpp v7, v50, v234 row_shr:2 row_mask:0xf bank_mask:0xf
	v_fmac_f32_dpp v7, v2, v234 row_shl:14 row_mask:0xf bank_mask:0xf
	v_fmac_f32_dpp v7, v50, v240 row_shr:1 row_mask:0xf bank_mask:0xf
	v_fmac_f32_dpp v7, v2, v240 row_shl:15 row_mask:0xf bank_mask:0xf
	v_fmac_f32_e32 v7, v50, v244
	v_mov_b32_e32 v6, v249
	v_fmac_f32_dpp v6, v51, v235 row_shr:2 row_mask:0xf bank_mask:0xf
	v_fmac_f32_dpp v6, v3, v235 row_shl:14 row_mask:0xf bank_mask:0xf
	v_fmac_f32_dpp v6, v51, v241 row_shr:1 row_mask:0xf bank_mask:0xf
	v_fmac_f32_dpp v6, v3, v241 row_shl:15 row_mask:0xf bank_mask:0xf
	v_fmac_f32_e32 v6, v51, v245
	v_mov_b32_e32 v46, v192
	v_mov_b32_e32 v47, v192
	v_pk_mul_f32 v[64:65], v[12:13], v[46:47]
	v_mov_b32_e32 v8, v250
	v_fmac_f32_dpp v8, v52, v236 row_shr:2 row_mask:0xf bank_mask:0xf
	v_fmac_f32_dpp v8, v4, v236 row_shl:14 row_mask:0xf bank_mask:0xf
	v_fmac_f32_dpp v8, v52, v242 row_shr:1 row_mask:0xf bank_mask:0xf
	v_fmac_f32_dpp v8, v4, v242 row_shl:15 row_mask:0xf bank_mask:0xf
	v_fmac_f32_e32 v8, v52, v246
	v_mov_b32_e32 v9, v251
	v_fmac_f32_dpp v9, v53, v237 row_shr:2 row_mask:0xf bank_mask:0xf
	v_fmac_f32_dpp v9, v5, v237 row_shl:14 row_mask:0xf bank_mask:0xf
	v_fmac_f32_dpp v9, v53, v243 row_shr:1 row_mask:0xf bank_mask:0xf
	v_fmac_f32_dpp v9, v5, v243 row_shl:15 row_mask:0xf bank_mask:0xf
	v_fmac_f32_e32 v9, v53, v247
	v_mov_b32_e32 v11, v248
	v_fmac_f32_dpp v11, v2, v234 row_shr:2 row_mask:0xf bank_mask:0xf
	v_fmac_f32_dpp v11, v76, v234 row_shl:14 row_mask:0xf bank_mask:0xf
	v_fmac_f32_dpp v11, v2, v240 row_shr:1 row_mask:0xf bank_mask:0xf
	v_fmac_f32_dpp v11, v76, v240 row_shl:15 row_mask:0xf bank_mask:0xf
	v_fmac_f32_e32 v11, v2, v244
	s_waitcnt lgkmcnt(0)
	v_cndmask_b32_e64 v17, v45, v17, s[8:9]
	v_mov_b32_e32 v2, v3
	v_mov_b32_e32 v10, v249
	s_nop 0
	v_fmac_f32_dpp v10, v2, v235 row_shr:2 row_mask:0xf bank_mask:0xf
	v_fmac_f32_dpp v10, v77, v235 row_shl:14 row_mask:0xf bank_mask:0xf
	v_fmac_f32_dpp v10, v2, v241 row_shr:1 row_mask:0xf bank_mask:0xf
	v_fmac_f32_dpp v10, v77, v241 row_shl:15 row_mask:0xf bank_mask:0xf
	v_fmac_f32_e32 v10, v2, v245
	v_mov_b32_e32 v12, v250
	v_fmac_f32_dpp v12, v4, v236 row_shr:2 row_mask:0xf bank_mask:0xf
	v_fmac_f32_dpp v12, v74, v236 row_shl:14 row_mask:0xf bank_mask:0xf
	v_fmac_f32_dpp v12, v4, v242 row_shr:1 row_mask:0xf bank_mask:0xf
	v_fmac_f32_dpp v12, v74, v242 row_shl:15 row_mask:0xf bank_mask:0xf
	v_fmac_f32_e32 v12, v4, v246
	v_mov_b32_e32 v4, v5
	v_mov_b32_e32 v13, v251
	s_nop 0
	v_fmac_f32_dpp v13, v4, v237 row_shr:2 row_mask:0xf bank_mask:0xf
	v_fmac_f32_dpp v13, v75, v237 row_shl:14 row_mask:0xf bank_mask:0xf
	v_fmac_f32_dpp v13, v4, v243 row_shr:1 row_mask:0xf bank_mask:0xf
	v_fmac_f32_dpp v13, v75, v243 row_shl:15 row_mask:0xf bank_mask:0xf
	v_fmac_f32_e32 v13, v4, v247
	v_mov_b32_e32 v47, v248
	v_fmac_f32_dpp v47, v76, v234 row_shr:2 row_mask:0xf bank_mask:0xf
	v_fmac_f32_dpp v47, v72, v234 row_shl:14 row_mask:0xf bank_mask:0xf
	v_fmac_f32_dpp v47, v76, v240 row_shr:1 row_mask:0xf bank_mask:0xf
	v_fmac_f32_dpp v47, v72, v240 row_shl:15 row_mask:0xf bank_mask:0xf
	v_fmac_f32_e32 v47, v76, v244
	v_mov_b32_e32 v46, v249
	v_fmac_f32_dpp v46, v77, v235 row_shr:2 row_mask:0xf bank_mask:0xf
	v_fmac_f32_dpp v46, v73, v235 row_shl:14 row_mask:0xf bank_mask:0xf
	v_fmac_f32_dpp v46, v77, v241 row_shr:1 row_mask:0xf bank_mask:0xf
	v_fmac_f32_dpp v46, v73, v241 row_shl:15 row_mask:0xf bank_mask:0xf
	v_fmac_f32_e32 v46, v77, v245
	v_mov_b32_e32 v50, v250
	v_fmac_f32_dpp v50, v74, v236 row_shr:2 row_mask:0xf bank_mask:0xf
	v_fmac_f32_dpp v50, v64, v236 row_shl:14 row_mask:0xf bank_mask:0xf
	v_fmac_f32_dpp v50, v74, v242 row_shr:1 row_mask:0xf bank_mask:0xf
	v_fmac_f32_dpp v50, v64, v242 row_shl:15 row_mask:0xf bank_mask:0xf
	v_fmac_f32_e32 v50, v74, v246
	v_mov_b32_e32 v51, v251
	v_fmac_f32_dpp v51, v75, v237 row_shr:2 row_mask:0xf bank_mask:0xf
	v_fmac_f32_dpp v51, v65, v237 row_shl:14 row_mask:0xf bank_mask:0xf
	v_fmac_f32_dpp v51, v75, v243 row_shr:1 row_mask:0xf bank_mask:0xf
	v_fmac_f32_dpp v51, v65, v243 row_shl:15 row_mask:0xf bank_mask:0xf
	v_fmac_f32_e32 v51, v75, v247
	v_cndmask_b32_e64 v4, v43, v15, s[8:9]
	v_cndmask_b32_e64 v3, v42, v14, s[8:9]
	v_cndmask_b32_e64 v2, v44, v16, s[8:9]
	v_mov_b32_e32 v252, v248
	v_fmac_f32_dpp v252, v72, v234 row_shr:2 row_mask:0xf bank_mask:0xf
	v_fmac_f32_dpp v252, v3, v234 row_shl:14 row_mask:0xf bank_mask:0xf
	v_fmac_f32_dpp v252, v72, v240 row_shr:1 row_mask:0xf bank_mask:0xf
	v_fmac_f32_dpp v252, v3, v240 row_shl:15 row_mask:0xf bank_mask:0xf
	v_fmac_f32_e32 v252, v72, v244
	v_mov_b32_e32 v231, v249
	v_fmac_f32_dpp v231, v73, v235 row_shr:2 row_mask:0xf bank_mask:0xf
	v_fmac_f32_dpp v231, v4, v235 row_shl:14 row_mask:0xf bank_mask:0xf
	v_fmac_f32_dpp v231, v73, v241 row_shr:1 row_mask:0xf bank_mask:0xf
	v_fmac_f32_dpp v231, v4, v241 row_shl:15 row_mask:0xf bank_mask:0xf
	v_fmac_f32_e32 v231, v73, v245
	v_mov_b32_e32 v15, v250
	v_fmac_f32_dpp v15, v64, v236 row_shr:2 row_mask:0xf bank_mask:0xf
	v_fmac_f32_dpp v15, v2, v236 row_shl:14 row_mask:0xf bank_mask:0xf
	v_fmac_f32_dpp v15, v64, v242 row_shr:1 row_mask:0xf bank_mask:0xf
	v_fmac_f32_dpp v15, v2, v242 row_shl:15 row_mask:0xf bank_mask:0xf
	v_fmac_f32_e32 v15, v64, v246
	v_mov_b32_e32 v27, v231
	v_mov_b32_e32 v26, v252
	v_mov_b32_e32 v28, v251
	v_fmac_f32_dpp v28, v65, v237 row_shr:2 row_mask:0xf bank_mask:0xf
; __device__ __forceinline__ unsigned cvt_pk_bf16(float lo, float hi) { unsigned r; asm volatile("v_cvt_pk_bf16_f32 %0, %1, %2" : "=v"(r) : "v"(lo), "v"(hi)); return r; }
;     __device__ __forceinline__ void operator()(f32x4 (&acc)[2][2][4][2], const Unit& u, int ui, int wr, int wc, int fr_, int fq_) const {
;     ...
;                     for (int m = 3; m >= 0; --m) { f32x4 cur = acc[ai][bj][m][n], res;
; #pragma unroll
;                         for (int j = 0; j < 4; ++j) { const float c = cur[j]; const float pv = (m > 0) ? acc[ai][bj][m > 0 ? m - 1 : 0][n][j] : (fr == 15 ? c63[j] : c62[j]); float t1, t2;
;                             asm volatile("s_nop 1\n\tv_mov_b32_dpp %0, %3 row_ror:1 row_mask:0xf bank_mask:0xf\n\tv_mov_b32_dpp %1, %3 row_ror:2 row_mask:0xf bank_mask:0xf\n\t"
;                                          "v_mov_b32_dpp %0, %2 row_shr:1 row_mask:0xf bank_mask:0xf\n\tv_mov_b32_dpp %1, %2 row_shr:2 row_mask:0xf bank_mask:0xf"
;                                          : "=&v"(t1), "=&v"(t2) : "v"(c), "v"(pv));
;                             res[j] = bb[j] + w0[j] * t2 + w1[j] * t1 + w2[j] * c; }
;                         asm volatile("" : "+v"(res[0]), "+v"(res[1]), "+v"(res[2]), "+v"(res[3]));
;                         acc[ai][bj][m][n] = res; } }
;                 asm volatile("" ::: "memory"); }
;         const int row0 = u.pm * BM + wr * 64 + fr;
; #pragma unroll
;         for (int ai = 0; ai < 2; ++ai)
; #pragma unroll
;             for (int m = 0; m < 4; ++m) { float gv[8];
; #pragma unroll
;                 for (int n = 0; n < 2; ++n)
; #pragma unroll
;                     for (int j = 0; j < 4; ++j) { const float g = acc[ai][0][m][n][j], up = acc[ai][1][m][n][j]; gv[n * 4 + j] = g * __builtin_amdgcn_rcpf(1.0f + __builtin_amdgcn_exp2f(g * -1.4426950408889634f)) * up; }
;                 u32x4 w; w.x = cvt_pk_bf16(gv[0], gv[1]); w.y = cvt_pk_bf16(gv[2], gv[3]); w.z = cvt_pk_bf16(gv[4], gv[5]); w.w = cvt_pk_bf16(gv[6], gv[7]);
;                 *(u32x4*)(G + (size_t)(row0 + ai * HALF + m * 16) * 2816 + fbase) = w; asm volatile("" ::: "memory"); }
	v_fmac_f32_dpp v28, v17, v237 row_shl:14 row_mask:0xf bank_mask:0xf
	v_fmac_f32_dpp v28, v65, v243 row_shr:1 row_mask:0xf bank_mask:0xf
	v_fmac_f32_dpp v28, v17, v243 row_shl:15 row_mask:0xf bank_mask:0xf
	v_fmac_f32_e32 v28, v65, v247
	v_mul_f32_e32 v22, s98, v123
	v_mul_f32_e32 v2, s98, v223
	v_mul_f32_e32 v3, s98, v224
	v_exp_f32_e32 v2, v2
	v_exp_f32_e32 v3, v3
	v_mul_f32_e32 v4, s98, v221
	v_mul_f32_e32 v5, s98, v222
	v_mul_f32_e32 v16, s98, v126
	v_mul_f32_e32 v17, s98, v122
	v_exp_f32_e32 v22, v22
	v_mul_f32_e32 v23, s98, v124
	v_exp_f32_e32 v4, v4
	v_exp_f32_e32 v5, v5
	v_exp_f32_e32 v16, v16
	v_exp_f32_e32 v17, v17
	v_exp_f32_e32 v23, v23
	v_add_f32_e32 v2, 1.0, v2
	v_add_f32_e32 v3, 1.0, v3
	v_add_f32_e32 v22, 1.0, v22
	v_rcp_f32_e32 v2, v2
	v_rcp_f32_e32 v3, v3
	v_add_f32_e32 v4, 1.0, v4
	v_add_f32_e32 v5, 1.0, v5
	v_add_f32_e32 v16, 1.0, v16
	v_add_f32_e32 v17, 1.0, v17
	v_rcp_f32_e32 v22, v22
	v_add_f32_e32 v23, 1.0, v23
	v_rcp_f32_e32 v4, v4
	v_rcp_f32_e32 v5, v5
	v_rcp_f32_e32 v16, v16
	v_rcp_f32_e32 v17, v17
	v_rcp_f32_e32 v23, v23
	s_lshl_b32 s0, s76, 8
	v_mul_f32_e32 v2, v223, v2
	v_mul_f32_e32 v3, v224, v3
	v_mul_f32_e32 v22, v123, v22
	s_add_i32 s0, s0, s68
	v_mul_f32_e32 v2, v2, v97
	v_mul_f32_e32 v3, v3, v96
	v_mul_f32_e32 v4, v221, v4
	v_mul_f32_e32 v5, v222, v5
	v_mul_f32_e32 v16, v126, v16
	v_mul_f32_e32 v17, v122, v17
	v_mul_f32_e32 v25, v22, v59
	v_mul_f32_e32 v22, v124, v23
	v_add_u32_e32 v14, s0, v210
	v_mul_f32_e32 v4, v4, v95
	v_mul_f32_e32 v5, v5, v94
	v_mul_f32_e32 v16, v16, v62
	v_mul_f32_e32 v17, v17, v58
	v_mul_f32_e32 v29, v22, v60
	v_cvt_pk_bf16_f32 v22, v2, v3
	v_mov_b64_e32 v[2:3], s[38:39]
	v_cvt_pk_bf16_f32 v23, v4, v5
	v_cvt_pk_bf16_f32 v24, v16, v17
	v_mad_i64_i32 v[16:17], s[0:1], v14, s83, v[2:3]
	v_lshlrev_b64 v[4:5], 1, v[186:187]
	v_lshl_add_u64 v[16:17], v[16:17], 0, v[4:5]
	v_cvt_pk_bf16_f32 v25, v25, v29
	global_store_dwordx4 v[16:17], v[22:25], off
	v_mul_f32_e32 v29, s98, v218
	v_exp_f32_e32 v29, v29
	v_mul_f32_e32 v22, s98, v217
	v_exp_f32_e32 v22, v22
	v_mul_f32_e32 v23, s98, v219
	v_exp_f32_e32 v23, v23
	v_mul_f32_e32 v24, s98, v225
	v_add_f32_e32 v22, 1.0, v22
	v_rcp_f32_e32 v22, v22
	v_add_f32_e32 v23, 1.0, v23
	v_rcp_f32_e32 v23, v23
	v_exp_f32_e32 v24, v24
	v_mul_f32_e32 v22, v217, v22
	v_mul_f32_e32 v25, v22, v108
	v_mul_f32_e32 v22, v219, v23
	v_add_f32_e32 v23, 1.0, v24
	v_mul_f32_e32 v34, s98, v220
	v_rcp_f32_e32 v23, v23
	v_mul_f32_e32 v24, s98, v144
	v_exp_f32_e32 v34, v34
	v_exp_f32_e32 v24, v24
	v_add_f32_e32 v16, 1.0, v29
	v_mul_f32_e32 v29, v22, v109
	v_mul_f32_e32 v22, v225, v23
	v_mul_f32_e32 v23, s98, v145
	v_add_f32_e32 v17, 1.0, v34
	v_mul_f32_e32 v34, v22, v69
	v_add_f32_e32 v22, 1.0, v24
	v_exp_f32_e32 v23, v23
	v_mul_f32_e32 v24, s98, v226
	v_exp_f32_e32 v24, v24
	v_rcp_f32_e32 v22, v22
	v_add_f32_e32 v23, 1.0, v23
	v_rcp_f32_e32 v16, v16
	v_rcp_f32_e32 v23, v23
	v_add_f32_e32 v24, 1.0, v24
	v_rcp_f32_e32 v17, v17
	v_rcp_f32_e32 v24, v24
	v_mul_f32_e32 v22, v144, v22
	v_mul_f32_e32 v16, v218, v16
	v_mul_f32_e32 v35, v22, v67
	v_mul_f32_e32 v22, v145, v23
	v_mul_f32_e32 v16, v16, v127
	v_mul_f32_e32 v17, v220, v17
	v_mul_f32_e32 v36, v22, v68
	v_mul_f32_e32 v22, v226, v24
	v_mul_f32_e32 v17, v17, v125
	v_mul_f32_e32 v37, v22, v70
	v_cvt_pk_bf16_f32 v22, v16, v17
	v_add_u32_e32 v16, 16, v14
	v_mad_i64_i32 v[16:17], s[0:1], v16, s83, v[2:3]
	v_lshl_add_u64 v[16:17], v[16:17], 0, v[4:5]
	v_cvt_pk_bf16_f32 v23, v25, v29
	v_cvt_pk_bf16_f32 v24, v34, v35
	v_cvt_pk_bf16_f32 v25, v36, v37
	global_store_dwordx4 v[16:17], v[22:25], off
	v_mul_f32_e32 v29, s98, v213
	v_exp_f32_e32 v29, v29
	v_mul_f32_e32 v22, s98, v154
	v_exp_f32_e32 v22, v22
	v_mul_f32_e32 v23, s98, v214
	v_exp_f32_e32 v23, v23
	v_mul_f32_e32 v24, s98, v142
	v_add_f32_e32 v22, 1.0, v22
	v_rcp_f32_e32 v22, v22
	v_add_f32_e32 v23, 1.0, v23
	v_rcp_f32_e32 v23, v23
	v_exp_f32_e32 v24, v24
	v_mul_f32_e32 v22, v154, v22
	v_mul_f32_e32 v25, v22, v100
	v_mul_f32_e32 v22, v214, v23
	v_add_f32_e32 v23, 1.0, v24
	v_mul_f32_e32 v34, s98, v216
	v_rcp_f32_e32 v23, v23
	v_mul_f32_e32 v24, s98, v136
	v_exp_f32_e32 v34, v34
	v_exp_f32_e32 v24, v24
	v_add_f32_e32 v16, 1.0, v29
	v_mul_f32_e32 v29, v22, v101
	v_mul_f32_e32 v22, v142, v23
	v_mul_f32_e32 v23, s98, v137
	v_add_f32_e32 v17, 1.0, v34
	v_mul_f32_e32 v34, v22, v56
	v_add_f32_e32 v22, 1.0, v24
	v_exp_f32_e32 v23, v23
	v_mul_f32_e32 v24, s98, v143
	v_exp_f32_e32 v24, v24
	v_rcp_f32_e32 v22, v22
	v_add_f32_e32 v23, 1.0, v23
	v_rcp_f32_e32 v16, v16
	v_rcp_f32_e32 v23, v23
	v_add_f32_e32 v24, 1.0, v24
	v_rcp_f32_e32 v17, v17
	v_rcp_f32_e32 v24, v24
	v_mul_f32_e32 v22, v136, v22
	v_mul_f32_e32 v16, v213, v16
	v_mul_f32_e32 v30, v22, v30
	v_mul_f32_e32 v22, v137, v23
	v_mul_f32_e32 v16, v16, v107
	v_mul_f32_e32 v17, v216, v17
	v_mul_f32_e32 v31, v22, v31
	v_mul_f32_e32 v22, v143, v24
	v_mul_f32_e32 v17, v17, v105
	v_mul_f32_e32 v35, v22, v66
	v_cvt_pk_bf16_f32 v22, v16, v17
	v_add_u32_e32 v16, 32, v14
	v_mad_i64_i32 v[16:17], s[0:1], v16, s83, v[2:3]
	v_cvt_pk_bf16_f32 v23, v25, v29
	v_cvt_pk_bf16_f32 v24, v34, v30
	v_lshl_add_u64 v[16:17], v[16:17], 0, v[4:5]
	v_cvt_pk_bf16_f32 v25, v31, v35
	global_store_dwordx4 v[16:17], v[22:25], off
	v_mul_f32_e32 v29, s98, v211
	v_exp_f32_e32 v29, v29
	v_mul_f32_e32 v24, s98, v133
	v_exp_f32_e32 v24, v24
	v_mul_f32_e32 v25, s98, v131
	v_exp_f32_e32 v25, v25
	v_mul_f32_e32 v30, s98, v212
	v_add_f32_e32 v24, 1.0, v24
	v_rcp_f32_e32 v24, v24
	v_exp_f32_e32 v30, v30
	v_add_f32_e32 v16, 1.0, v29
	v_mul_f32_e32 v22, s98, v152
	v_mul_f32_e32 v24, v133, v24
	v_mul_f32_e32 v20, v24, v20
	v_add_f32_e32 v24, 1.0, v25
	v_mul_f32_e32 v25, s98, v132
; __device__ __forceinline__ unsigned cvt_pk_bf16(float lo, float hi) { unsigned r; asm volatile("v_cvt_pk_bf16_f32 %0, %1, %2" : "=v"(r) : "v"(lo), "v"(hi)); return r; }
;     __device__ __forceinline__ void operator()(f32x4 (&acc)[2][2][4][2], const Unit& u, int ui, int wr, int wc, int fr_, int fq_) const {
;     ...
;         const int row0 = u.pm * BM + wr * 64 + fr;
; #pragma unroll
;         for (int ai = 0; ai < 2; ++ai)
; #pragma unroll
;             for (int m = 0; m < 4; ++m) { float gv[8];
; #pragma unroll
;                 for (int n = 0; n < 2; ++n)
; #pragma unroll
;                     for (int j = 0; j < 4; ++j) { const float g = acc[ai][0][m][n][j], up = acc[ai][1][m][n][j]; gv[n * 4 + j] = g * __builtin_amdgcn_rcpf(1.0f + __builtin_amdgcn_exp2f(g * -1.4426950408889634f)) * up; }
;                 u32x4 w; w.x = cvt_pk_bf16(gv[0], gv[1]); w.y = cvt_pk_bf16(gv[2], gv[3]); w.z = cvt_pk_bf16(gv[4], gv[5]); w.w = cvt_pk_bf16(gv[6], gv[7]);
;                 *(u32x4*)(G + (size_t)(row0 + ai * HALF + m * 16) * 2816 + fbase) = w; asm volatile("" ::: "memory"); }
	v_mul_f32_e32 v23, s98, v153
	v_exp_f32_e32 v25, v25
	v_mul_f32_e32 v29, s98, v135
	v_exp_f32_e32 v22, v22
	v_exp_f32_e32 v23, v23
	v_exp_f32_e32 v29, v29
	v_add_f32_e32 v17, 1.0, v30
	v_rcp_f32_e32 v24, v24
	v_add_f32_e32 v25, 1.0, v25
	v_rcp_f32_e32 v16, v16
	v_rcp_f32_e32 v17, v17
	v_add_f32_e32 v22, 1.0, v22
	v_add_f32_e32 v23, 1.0, v23
	v_rcp_f32_e32 v25, v25
	v_add_f32_e32 v29, 1.0, v29
	v_rcp_f32_e32 v22, v22
	v_rcp_f32_e32 v23, v23
	v_rcp_f32_e32 v29, v29
	v_mul_f32_e32 v24, v131, v24
	v_mul_f32_e32 v16, v211, v16
	v_mul_f32_e32 v17, v212, v17
	v_mul_f32_e32 v18, v24, v18
	v_mul_f32_e32 v24, v132, v25
	v_mul_f32_e32 v16, v16, v104
	v_mul_f32_e32 v17, v17, v103
	v_mul_f32_e32 v22, v152, v22
	v_mul_f32_e32 v23, v153, v23
	v_mul_f32_e32 v19, v24, v19
	v_mul_f32_e32 v24, v135, v29
	v_mul_f32_e32 v22, v22, v98
	v_mul_f32_e32 v23, v23, v99
	v_mul_f32_e32 v21, v24, v21
	v_cvt_pk_bf16_f32 v16, v16, v17
	v_cvt_pk_bf16_f32 v17, v22, v23
	v_cvt_pk_bf16_f32 v18, v20, v18
	v_add_u32_e32 v20, 48, v14
	v_cvt_pk_bf16_f32 v19, v19, v21
	v_mad_i64_i32 v[20:21], s[0:1], v20, s83, v[2:3]
	v_lshl_add_u64 v[20:21], v[20:21], 0, v[4:5]
	global_store_dwordx4 v[20:21], v[16:19], off
	v_mul_f32_e32 v22, s98, v102
	v_mul_f32_e32 v21, s98, v106
	v_mul_f32_e32 v16, s98, v134
	v_mul_f32_e32 v17, s98, v130
	v_mul_f32_e32 v18, s98, v32
	v_exp_f32_e32 v16, v16
	v_exp_f32_e32 v17, v17
	v_exp_f32_e32 v18, v18
	v_mul_f32_e32 v19, s98, v33
	v_exp_f32_e32 v22, v22
	v_exp_f32_e32 v19, v19
	v_exp_f32_e32 v21, v21
	v_mul_f32_e32 v23, s98, v48
	v_exp_f32_e32 v23, v23
	v_mul_f32_e32 v24, s98, v49
	v_add_f32_e32 v16, 1.0, v16
	v_add_f32_e32 v17, 1.0, v17
	v_add_f32_e32 v18, 1.0, v18
	v_add_f32_e32 v22, 1.0, v22
	v_exp_f32_e32 v24, v24
	v_rcp_f32_e32 v16, v16
	v_rcp_f32_e32 v17, v17
	v_rcp_f32_e32 v18, v18
	v_add_f32_e32 v19, 1.0, v19
	v_add_f32_e32 v21, 1.0, v21
	v_rcp_f32_e32 v22, v22
	v_rcp_f32_e32 v19, v19
	v_rcp_f32_e32 v21, v21
	v_add_f32_e32 v23, 1.0, v23
	v_rcp_f32_e32 v23, v23
	v_add_f32_e32 v24, 1.0, v24
	v_mul_f32_e32 v16, v134, v16
	v_mul_f32_e32 v17, v130, v17
	v_mul_f32_e32 v18, v32, v18
	v_mul_f32_e32 v22, v102, v22
	v_rcp_f32_e32 v24, v24
	v_mul_f32_e32 v16, v16, v78
	v_mul_f32_e32 v17, v17, v55
	v_mul_f32_e32 v18, v18, v54
	v_mul_f32_e32 v19, v33, v19
	v_mul_f32_e32 v21, v106, v21
	v_mul_f32_e32 v22, v22, v27
	v_mul_f32_e32 v19, v19, v57
	v_mul_f32_e32 v21, v21, v26
	v_cvt_pk_bf16_f32 v16, v16, v17
	v_cvt_pk_bf16_f32 v17, v18, v19
	v_cvt_pk_bf16_f32 v18, v21, v22
	v_mul_f32_e32 v22, s98, v215
	v_add_u32_e32 v20, 0x80, v14
	v_mul_f32_e32 v23, v48, v23
	v_exp_f32_e32 v22, v22
	v_mul_f32_e32 v15, v23, v15
	v_mul_f32_e32 v23, v49, v24
	v_mad_i64_i32 v[20:21], s[0:1], v20, s83, v[2:3]
	v_mul_f32_e32 v23, v23, v28
	v_cvt_pk_bf16_f32 v19, v15, v23
	v_lshl_add_u64 v[20:21], v[20:21], 0, v[4:5]
	v_mul_f32_e32 v15, s98, v151
	v_exp_f32_e32 v15, v15
	global_store_dwordx4 v[20:21], v[16:19], off
	v_mul_f32_e32 v20, s98, v118
	v_mul_f32_e32 v21, s98, v119
	v_mul_f32_e32 v17, s98, v150
	v_mul_f32_e32 v18, s98, v155
	v_mul_f32_e32 v19, s98, v120
	v_add_f32_e32 v16, 1.0, v22
	v_exp_f32_e32 v17, v17
	v_exp_f32_e32 v18, v18
	v_exp_f32_e32 v19, v19
	v_exp_f32_e32 v20, v20
	v_exp_f32_e32 v21, v21
	v_mul_f32_e32 v22, s98, v121
	v_exp_f32_e32 v22, v22
	v_add_f32_e32 v15, 1.0, v15
	v_rcp_f32_e32 v15, v15
	v_rcp_f32_e32 v16, v16
	v_add_f32_e32 v17, 1.0, v17
	v_add_f32_e32 v18, 1.0, v18
	v_add_f32_e32 v19, 1.0, v19
	v_add_f32_e32 v20, 1.0, v20
	v_add_f32_e32 v21, 1.0, v21
	v_rcp_f32_e32 v17, v17
	v_rcp_f32_e32 v18, v18
	v_rcp_f32_e32 v19, v19
	v_rcp_f32_e32 v20, v20
	v_rcp_f32_e32 v21, v21
	v_add_f32_e32 v22, 1.0, v22
	v_rcp_f32_e32 v22, v22
	v_mul_f32_e32 v15, v151, v15
	v_mul_f32_e32 v16, v215, v16
	v_mul_f32_e32 v15, v15, v93
	v_mul_f32_e32 v16, v16, v92
	v_mul_f32_e32 v17, v150, v17
	v_mul_f32_e32 v18, v155, v18
	v_mul_f32_e32 v19, v120, v19
	v_mul_f32_e32 v20, v118, v20
	v_mul_f32_e32 v21, v119, v21
; __device__ __forceinline__ unsigned cvt_pk_bf16(float lo, float hi) { unsigned r; asm volatile("v_cvt_pk_bf16_f32 %0, %1, %2" : "=v"(r) : "v"(lo), "v"(hi)); return r; }
; #define PG8_BAR __builtin_amdgcn_s_barrier()
;     __device__ __forceinline__ void operator()(f32x4 (&acc)[2][2][4][2], const Unit& u, int ui, int wr, int wc, int fr_, int fq_) const {
;     ...
;         const int row0 = u.pm * BM + wr * 64 + fr;
; #pragma unroll
;         for (int ai = 0; ai < 2; ++ai)
; #pragma unroll
;             for (int m = 0; m < 4; ++m) { float gv[8];
; #pragma unroll
;                 for (int n = 0; n < 2; ++n)
; #pragma unroll
;                     for (int j = 0; j < 4; ++j) { const float g = acc[ai][0][m][n][j], up = acc[ai][1][m][n][j]; gv[n * 4 + j] = g * __builtin_amdgcn_rcpf(1.0f + __builtin_amdgcn_exp2f(g * -1.4426950408889634f)) * up; }
;                 u32x4 w; w.x = cvt_pk_bf16(gv[0], gv[1]); w.y = cvt_pk_bf16(gv[2], gv[3]); w.z = cvt_pk_bf16(gv[4], gv[5]); w.w = cvt_pk_bf16(gv[6], gv[7]);
;                 *(u32x4*)(G + (size_t)(row0 + ai * HALF + m * 16) * 2816 + fbase) = w; asm volatile("" ::: "memory"); }
; template <class Epi, class Sched, bool ALIGN_EPI = false, bool SP2 = false>
; __device__ __forceinline__ void gemm_phase(PG8_LAS unsigned char* lds, const Gemm g, const Sched& S, const Epi& E) {
;     ...
;         if constexpr (ALIGN_EPI) { if (wr == 0) PG8_BAR; }
;         if constexpr (!Epi::AFTER_DRAIN) { E(acc, cur, ui, wr, wc, fr, fq); S.done(cur); }
;         if (!has_next) break;
; #pragma unroll
;         for (int a = 0; a < 2; ++a)
; #pragma unroll
;             for (int b = 0; b < 2; ++b)
; #pragma unroll
;                 for (int m = 0; m < 4; ++m)
; #pragma unroll
;                     for (int n = 0; n < 2; ++n) acc[a][b][m][n] = (f32x4){0.f, 0.f, 0.f, 0.f};
;         cur = nxt; cA = nA; cB = nB; ++ui;
;         if constexpr (ALIGN_EPI) { if (wr == 1) PG8_BAR; }
	v_mul_f32_e32 v17, v17, v90
	v_mul_f32_e32 v18, v18, v91
	v_mul_f32_e32 v19, v19, v47
	v_mul_f32_e32 v20, v20, v46
	v_mul_f32_e32 v21, v21, v50
	v_mul_f32_e32 v22, v121, v22
	v_cvt_pk_bf16_f32 v16, v15, v16
	v_add_u32_e32 v15, 0x90, v14
	v_mul_f32_e32 v22, v22, v51
	v_cvt_pk_bf16_f32 v17, v17, v18
	v_cvt_pk_bf16_f32 v18, v19, v20
	v_cvt_pk_bf16_f32 v19, v21, v22
	v_mad_i64_i32 v[20:21], s[0:1], v15, s83, v[2:3]
	v_lshl_add_u64 v[20:21], v[20:21], 0, v[4:5]
	global_store_dwordx4 v[20:21], v[16:19], off
	v_mul_f32_e32 v20, s98, v114
	v_exp_f32_e32 v20, v20
	v_mul_f32_e32 v19, s98, v116
	v_exp_f32_e32 v19, v19
	v_mul_f32_e32 v15, s98, v147
	v_exp_f32_e32 v15, v15
	v_mul_f32_e32 v22, s98, v149
	v_add_f32_e32 v19, 1.0, v19
	v_rcp_f32_e32 v19, v19
	v_mul_f32_e32 v17, s98, v146
	v_mul_f32_e32 v21, s98, v117
	v_exp_f32_e32 v22, v22
	v_mul_f32_e32 v19, v116, v19
	v_mul_f32_e32 v19, v19, v11
	v_add_f32_e32 v11, 1.0, v20
	v_mul_f32_e32 v20, s98, v115
	v_exp_f32_e32 v20, v20
	v_exp_f32_e32 v17, v17
	v_mul_f32_e32 v18, s98, v148
	v_exp_f32_e32 v21, v21
	v_exp_f32_e32 v18, v18
	v_add_f32_e32 v15, 1.0, v15
	v_rcp_f32_e32 v11, v11
	v_add_f32_e32 v20, 1.0, v20
	v_rcp_f32_e32 v15, v15
	v_add_f32_e32 v16, 1.0, v22
	v_add_f32_e32 v17, 1.0, v17
	v_rcp_f32_e32 v20, v20
	v_add_f32_e32 v21, 1.0, v21
	v_rcp_f32_e32 v16, v16
	v_rcp_f32_e32 v17, v17
	v_add_f32_e32 v18, 1.0, v18
	v_rcp_f32_e32 v21, v21
	v_rcp_f32_e32 v18, v18
	v_mul_f32_e32 v11, v114, v11
	v_mul_f32_e32 v15, v147, v15
	v_mul_f32_e32 v22, v11, v10
	v_mul_f32_e32 v10, v115, v20
	v_mul_f32_e32 v15, v15, v89
	v_mul_f32_e32 v16, v149, v16
	v_mul_f32_e32 v17, v146, v17
	v_mul_f32_e32 v20, v10, v12
	v_mul_f32_e32 v10, v117, v21
	v_mul_f32_e32 v16, v16, v88
	v_mul_f32_e32 v17, v17, v84
	v_mul_f32_e32 v18, v148, v18
	v_mul_f32_e32 v13, v10, v13
	v_cvt_pk_bf16_f32 v10, v15, v16
	v_add_u32_e32 v15, 0xa0, v14
	v_mul_f32_e32 v18, v18, v85
	v_cvt_pk_bf16_f32 v11, v17, v18
	v_mad_i64_i32 v[16:17], s[0:1], v15, s83, v[2:3]
	v_mul_f32_e32 v15, s98, v139
	v_exp_f32_e32 v15, v15
	v_lshl_add_u64 v[16:17], v[16:17], 0, v[4:5]
	v_cvt_pk_bf16_f32 v12, v19, v22
	v_cvt_pk_bf16_f32 v13, v20, v13
	global_store_dwordx4 v[16:17], v[10:13], off
	v_mul_f32_e32 v16, s98, v110
	v_exp_f32_e32 v16, v16
	v_add_f32_e32 v10, 1.0, v15
	v_mul_f32_e32 v15, s98, v112
	v_exp_f32_e32 v15, v15
	v_mul_f32_e32 v18, s98, v141
	v_mul_f32_e32 v17, s98, v113
	v_exp_f32_e32 v18, v18
	v_add_f32_e32 v15, 1.0, v15
	v_rcp_f32_e32 v15, v15
	v_exp_f32_e32 v17, v17
	v_mul_f32_e32 v12, s98, v138
	v_mul_f32_e32 v13, s98, v140
	v_mul_f32_e32 v15, v112, v15
	v_mul_f32_e32 v15, v15, v7
	v_add_f32_e32 v7, 1.0, v16
	v_mul_f32_e32 v16, s98, v111
	v_exp_f32_e32 v16, v16
	v_exp_f32_e32 v12, v12
	v_exp_f32_e32 v13, v13
	v_rcp_f32_e32 v7, v7
	v_add_f32_e32 v16, 1.0, v16
	v_rcp_f32_e32 v10, v10
	v_add_f32_e32 v11, 1.0, v18
	v_rcp_f32_e32 v16, v16
	v_add_f32_e32 v17, 1.0, v17
	v_rcp_f32_e32 v11, v11
	v_rcp_f32_e32 v17, v17
	v_add_f32_e32 v12, 1.0, v12
	v_add_f32_e32 v13, 1.0, v13
	v_mul_f32_e32 v7, v110, v7
	v_mul_f32_e32 v10, v139, v10
	v_rcp_f32_e32 v12, v12
	v_rcp_f32_e32 v13, v13
	v_mul_f32_e32 v18, v7, v6
	v_mul_f32_e32 v6, v111, v16
	v_mul_f32_e32 v10, v10, v87
	v_mul_f32_e32 v11, v141, v11
	v_mul_f32_e32 v16, v6, v8
	v_mul_f32_e32 v6, v113, v17
	v_mul_f32_e32 v11, v11, v86
	v_mul_f32_e32 v9, v6, v9
	v_cvt_pk_bf16_f32 v6, v10, v11
	v_add_u32_e32 v10, 0xb0, v14
	v_mad_i64_i32 v[2:3], s[0:1], v10, s83, v[2:3]
	v_mul_f32_e32 v12, v138, v12
	v_mul_f32_e32 v13, v140, v13
	v_lshl_add_u64 v[2:3], v[2:3], 0, v[4:5]
	v_mul_f32_e32 v12, v12, v82
	v_mul_f32_e32 v13, v13, v83
	v_cvt_pk_bf16_f32 v7, v12, v13
	v_cvt_pk_bf16_f32 v8, v15, v18
	v_cvt_pk_bf16_f32 v9, v16, v9
	global_store_dwordx4 v[2:3], v[6:9], off
	s_andn2_b64 vcc, exec, s[6:7]
	s_mov_b64 s[0:1], -1
	s_cbranch_vccnz .LBB0_1171
	s_andn2_b64 vcc, exec, s[16:17]
	s_cbranch_vccnz .LBB0_1170
	s_barrier
	s_branch .LBB0_1170

; __device__ __forceinline__ int opaque_tid() { int t = threadIdx.x; asm volatile("" : "+v"(t)); return t; }
; __device__ __forceinline__ unsigned pk2(float lo, float hi) { f32x2_t v = {lo, hi}; bf16x2_t b = __builtin_convertvector(v, bf16x2_t); return __builtin_bit_cast(unsigned, b); }
; __global__ void __launch_bounds__(NT, 2) trunk_fwd(Args args) {
;     ...
;             for (int i = 0; S.next(i, u); ++i) {
;                 const bool first = (u.pm % 32) == 0;
;                 for (int f = pg8::opaque_tid(); f < DFF; f += NT) { float cg0[2], cg1[2];
; #pragma unroll
;                     for (int part = 0; part < 2; ++part) { const int ch = part * DFF + f;
;                         const float um2 = first ? 0.f : HALO[(size_t)((u.pm - 1) * 4 + 2) * 5632 + ch], um1 = first ? 0.f : HALO[(size_t)((u.pm - 1) * 4 + 3) * 5632 + ch];
;                         const float u0 = HALO[(size_t)(u.pm * 4 + 0) * 5632 + ch], u1 = HALO[(size_t)(u.pm * 4 + 1) * 5632 + ch];
;                         const float w0 = cw[ch], w1 = cw[5632 + ch], w2 = cw[2 * 5632 + ch], bb = cb[ch];
;                         cg0[part] = bb + w0 * um2 + w1 * um1 + w2 * u0; cg1[part] = bb + w0 * um1 + w1 * u0 + w2 * u1; }
;                     const float g0 = cg0[0] / (1.0f + __expf(-cg0[0])) * cg0[1], g1 = cg1[0] / (1.0f + __expf(-cg1[0])) * cg1[1];
;                     GB[(size_t)(u.pm * 256) * DFF + f] = (bf16)(pk2(g0, 0.f) & 0xffffu); GB[(size_t)(u.pm * 256 + 1) * DFF + f] = (bf16)(pk2(g1, 0.f) & 0xffffu); }
.LBB0_1271:
	v_lshlrev_b64 v[12:13], 2, v[12:13]
	v_lshl_add_u64 v[26:27], s[20:21], 0, v[12:13]
	global_load_dword v38, v[26:27], off
	v_lshl_add_u64 v[26:27], s[22:23], 0, v[12:13]
	global_load_dword v39, v[26:27], off
	v_lshl_add_u64 v[26:27], s[6:7], 0, v[12:13]
	v_add_co_u32_e32 v28, vcc, 0x5000, v26
	v_lshl_add_u64 v[12:13], s[10:11], 0, v[12:13]
	global_load_dword v40, v[26:27], off
	v_addc_co_u32_e32 v29, vcc, 0, v27, vcc
	global_load_dword v41, v[12:13], off
	v_lshlrev_b64 v[10:11], 1, v[10:11]
	global_load_dword v42, v[28:29], off offset:2048
	v_add_co_u32_e32 v26, vcc, 0xb000, v26
	v_lshl_add_u64 v[2:3], v[2:3], 0, s[96:97]
	s_nop 0
	v_addc_co_u32_e32 v27, vcc, 0, v27, vcc
	global_load_dword v43, v[26:27], off
	s_waitcnt vmcnt(6)
	v_fma_f32 v17, v17, v20, v0
	v_fmac_f32_e32 v0, v15, v20
	v_fmac_f32_e32 v17, v15, v21
	v_fmac_f32_e32 v0, v18, v21
	v_fmac_f32_e32 v17, v18, v22
	v_fmac_f32_e32 v0, v19, v22
	v_lshl_add_u64 v[4:5], v[4:5], 0, s[84:85]
	v_lshl_add_u64 v[6:7], v[6:7], 0, s[96:97]
	v_lshl_add_u64 v[8:9], v[8:9], 0, s[84:85]
	s_waitcnt vmcnt(2)
	v_fma_f32 v13, v16, v40, v41
	v_fmac_f32_e32 v41, v14, v40
	s_waitcnt vmcnt(1)
	v_fmac_f32_e32 v13, v14, v42
	v_mul_f32_e32 v14, 0xbfb8aa3b, v17
	v_exp_f32_e32 v14, v14
	v_fmac_f32_e32 v41, v38, v42
	v_add_f32_e32 v14, 1.0, v14
	s_waitcnt vmcnt(0)
	v_fmac_f32_e32 v13, v38, v43
	v_div_scale_f32 v15, s[0:1], v14, v14, v17
	v_rcp_f32_e32 v16, v15
	v_fmac_f32_e32 v41, v39, v43
	v_fma_f32 v18, -v15, v16, 1.0
	v_fmac_f32_e32 v16, v18, v16
	v_div_scale_f32 v18, vcc, v17, v14, v17
	v_mul_f32_e32 v19, v18, v16
	v_fma_f32 v20, -v15, v19, v18
	v_fmac_f32_e32 v19, v20, v16
	v_fma_f32 v15, -v15, v19, v18
	v_div_fmas_f32 v15, v15, v16, v19
	v_div_fixup_f32 v14, v15, v14, v17
	v_mul_f32_e32 v13, v13, v14
	v_mul_f32_e32 v14, 0xbfb8aa3b, v0
	v_exp_f32_e32 v14, v14
	s_nop 0
	v_add_f32_e32 v14, 1.0, v14
	v_div_scale_f32 v15, s[0:1], v14, v14, v0
	v_rcp_f32_e32 v16, v15
	s_nop 0
	v_fma_f32 v17, -v15, v16, 1.0
	v_fmac_f32_e32 v16, v17, v16
	v_div_scale_f32 v17, vcc, v0, v14, v0
	v_mul_f32_e32 v18, v17, v16
	v_fma_f32 v19, -v15, v18, v17
	v_fmac_f32_e32 v18, v19, v16
	v_fma_f32 v15, -v15, v18, v17
	v_div_fmas_f32 v15, v15, v16, v18
	v_div_fixup_f32 v0, v15, v14, v0
	v_mul_f32_e32 v0, v41, v0
	v_cvt_pk_bf16_f32 v14, v13, s0
	v_lshl_add_u64 v[12:13], s[26:27], 0, v[10:11]
	v_cvt_pk_bf16_f32 v0, v0, s0
	v_lshl_add_u64 v[10:11], s[38:39], 0, v[10:11]
	global_store_short v[10:11], v0, off
	v_add_u32_e32 v0, 0xfffffe00, v2
	s_movk_i32 s0, 0x8ff
	v_cmp_lt_i32_e32 vcc, s0, v0
	s_or_b64 s[40:41], vcc, s[40:41]
	global_store_short v[12:13], v14, off
	s_andn2_b64 exec, exec, s[40:41]
	s_cbranch_execz .LBB0_1260
